# GEMM K-loops: removed s_setprio flips and the redundant post-barrier lgkmcnt(0) around each 32-MFMA block
# speedup vs baseline: 1.0090x; 1.0090x over previous
; #define PG8_STAGE(bufoff, gbase, voff) do { _Pragma("unroll") for (int _i = 0; _i < 2; ++_i) \
;         __builtin_amdgcn_global_load_lds((const unsigned*)((const char*)(gbase) + (voff)[_i]), (PG8_LAS unsigned*)(lds + (bufoff) + ldsw + _i * 8192), 16, 0, 0); } while (0)
; #define PG8_LDA(dst, b, h) do { _Pragma("unroll") for (int m = 0; m < 4; ++m) _Pragma("unroll") for (int k = 0; k < 2; ++k) dst[m][k] = *(const PG8_LAS bf16x8*)(lds + PG8_SA(b, h) + aoff + m * 2048 + k * 1024); } while (0)
; #define PG8_LDB(dst, b, h) do { _Pragma("unroll") for (int n = 0; n < 2; ++n) _Pragma("unroll") for (int k = 0; k < 2; ++k) dst[n][k] = *(const PG8_LAS bf16x8*)(lds + PG8_SB(b, h) + boff + n * 2048 + k * 1024); } while (0)
; #define PG8_MMA(ai, bj, At, Bt) do { __builtin_amdgcn_s_setprio(1); _Pragma("unroll") for (int m = 0; m < 4; ++m) _Pragma("unroll") for (int n = 0; n < 2; ++n) _Pragma("unroll") for (int k = 0; k < 2; ++k) \
;         acc[ai][bj][m][n] = __builtin_amdgcn_mfma_f32_16x16x32_f16(Bt[n][k], At[m][k], acc[ai][bj][m][n], 0, 0, 0); __builtin_amdgcn_s_setprio(0); } while (0)
; #define PG8_WAIT_V(n) asm volatile("s_waitcnt vmcnt(" #n ")" ::: "memory")
; #define PG8_WAIT_L(n) asm volatile("s_waitcnt lgkmcnt(" #n ")" ::: "memory")
; #define PG8_BAR __builtin_amdgcn_s_barrier()
; #define PG8_SCHED __builtin_amdgcn_sched_barrier(0)
; template <class Epi, class Sched, bool ALIGN_EPI = false, bool SP2 = false>
; __device__ __forceinline__ void gemm_phase(PG8_LAS unsigned char* lds, const Gemm g, const Sched& S, const Epi& E) {
;     ...
;         for (int t = 0; t < nt; t += 2) {
;             const bool last = (t == nt - 2);
;             const char* a1 = cA + (size_t)(t + 1) * kstep;
;             const char* a2 = last ? nA : cA + (size_t)(t + 2) * kstep; const char* b2 = last ? nB : cB + (size_t)(t + 2) * kstep;
;             const char* a3 = a2 + kstep; const char* b3 = b2 + kstep;
;             if (last && has_next) S.a_ready(nxt);
;             if constexpr (SP2) {
;             PG8_LDB(B0, 0, 0); PG8_LDB(B1, 0, 1); PG8_SCHED; PG8_LDA(At, 0, 0); PG8_STAGE(PG8_SA(1, 1), a1 + hstep, voffA);
;             PG8_WAIT_V(8); PG8_WAIT_L(0); PG8_BAR; PG8_MMA(0, 0, At, B0); PG8_MMA(0, 1, At, B1); PG8_BAR; PG8_SCHED;
;             PG8_LDA(At, 0, 1); PG8_STAGE(PG8_SB(0, 0), b2, voffB); PG8_STAGE(PG8_SB(0, 1), b2 + hstep, voffB); PG8_STAGE(PG8_SA(0, 0), a2, voffA);
.LBB0_185:
	s_add_u32 s12, s50, 0xfffc0080
	s_addc_u32 s13, s51, -1
	s_add_i32 s92, 0, 0x10000
	s_cmp_eq_u32 s83, 12
	s_cselect_b32 s25, s39, s13
	s_cselect_b32 s24, s73, s12
	s_cselect_b32 s23, s17, s82
	s_cselect_b32 s22, s76, s77
	s_add_i32 s12, 0, 0x14000
	v_add_u32_e32 v106, s92, v191
	v_add_u32_e32 v130, s12, v191
	ds_read_b128 v[94:97], v106
	ds_read_b128 v[98:101], v106 offset:1024
	ds_read_b128 v[102:105], v106 offset:2048
	ds_read_b128 v[106:109], v106 offset:3072
	ds_read_b128 v[114:117], v130
	ds_read_b128 v[118:121], v130 offset:1024
	ds_read_b128 v[126:129], v130 offset:2048
	ds_read_b128 v[130:133], v130 offset:3072
	v_lshl_add_u64 v[188:189], s[50:51], 0, v[172:173]
	s_add_i32 m0, s10, 0xc000
	ds_read_b128 v[176:179], v193
	ds_read_b128 v[180:183], v193 offset:1024
	ds_read_b128 v[184:187], v193 offset:2048
	ds_read_b128 v[196:199], v193 offset:3072
	ds_read_b128 v[200:203], v193 offset:4096
	ds_read_b128 v[204:207], v193 offset:5120
	ds_read_b128 v[218:221], v193 offset:6144
	ds_read_b128 v[222:225], v193 offset:7168
	global_load_lds_dwordx4 v[188:189], off
	v_lshl_add_u64 v[188:189], s[50:51], 0, v[174:175]
	s_add_i32 m0, s10, 0xe000
	s_nop 0
	global_load_lds_dwordx4 v[188:189], off
	s_waitcnt vmcnt(8)
	s_waitcnt lgkmcnt(0)
	s_barrier
	v_mfma_f32_16x16x32_f16 v[162:165], v[94:97], v[176:179], v[162:165]
	v_mfma_f32_16x16x32_f16 v[158:161], v[102:105], v[176:179], v[158:161]
	v_mfma_f32_16x16x32_f16 v[146:149], v[94:97], v[184:187], v[146:149]
	v_mfma_f32_16x16x32_f16 v[142:145], v[102:105], v[184:187], v[142:145]
	v_mfma_f32_16x16x32_f16 v[122:125], v[94:97], v[200:203], v[122:125]
	v_mfma_f32_16x16x32_f16 v[110:113], v[102:105], v[200:203], v[110:113]
	v_mfma_f32_16x16x32_f16 v[82:85], v[94:97], v[218:221], v[82:85]
	v_mfma_f32_16x16x32_f16 v[78:81], v[102:105], v[218:221], v[78:81]
	v_mfma_f32_16x16x32_f16 v[162:165], v[98:101], v[180:183], v[162:165]
	v_mfma_f32_16x16x32_f16 v[158:161], v[106:109], v[180:183], v[158:161]
	v_mfma_f32_16x16x32_f16 v[146:149], v[98:101], v[196:199], v[146:149]
	v_mfma_f32_16x16x32_f16 v[142:145], v[106:109], v[196:199], v[142:145]
	v_mfma_f32_16x16x32_f16 v[122:125], v[98:101], v[204:207], v[122:125]
	v_mfma_f32_16x16x32_f16 v[110:113], v[106:109], v[204:207], v[110:113]
	v_mfma_f32_16x16x32_f16 v[82:85], v[98:101], v[222:225], v[82:85]
	v_mfma_f32_16x16x32_f16 v[78:81], v[106:109], v[222:225], v[78:81]
	v_mfma_f32_16x16x32_f16 v[154:157], v[114:117], v[176:179], v[154:157]
	v_mfma_f32_16x16x32_f16 v[150:153], v[126:129], v[176:179], v[150:153]
	v_mfma_f32_16x16x32_f16 v[138:141], v[114:117], v[184:187], v[138:141]
	v_mfma_f32_16x16x32_f16 v[134:137], v[126:129], v[184:187], v[134:137]
	v_mfma_f32_16x16x32_f16 v[90:93], v[114:117], v[200:203], v[90:93]
	v_mfma_f32_16x16x32_f16 v[86:89], v[126:129], v[200:203], v[86:89]
	v_mfma_f32_16x16x32_f16 v[74:77], v[114:117], v[218:221], v[74:77]
	v_mfma_f32_16x16x32_f16 v[70:73], v[126:129], v[218:221], v[70:73]
	v_mfma_f32_16x16x32_f16 v[154:157], v[118:121], v[180:183], v[154:157]
	v_mfma_f32_16x16x32_f16 v[150:153], v[130:133], v[180:183], v[150:153]
	v_mfma_f32_16x16x32_f16 v[138:141], v[118:121], v[196:199], v[138:141]
	v_mfma_f32_16x16x32_f16 v[134:137], v[130:133], v[196:199], v[134:137]
	v_mfma_f32_16x16x32_f16 v[90:93], v[118:121], v[204:207], v[90:93]
	v_mfma_f32_16x16x32_f16 v[86:89], v[130:133], v[204:207], v[86:89]
	v_mfma_f32_16x16x32_f16 v[74:77], v[118:121], v[222:225], v[74:77]
	v_mfma_f32_16x16x32_f16 v[70:73], v[130:133], v[222:225], v[70:73]
	s_barrier
	s_add_i32 s13, s92, s5
	v_lshl_add_u64 v[188:189], s[22:23], 0, v[168:169]
	s_mov_b32 m0, s13
	ds_read_b128 v[176:179], v193 offset:16384
	ds_read_b128 v[180:183], v193 offset:17408
	ds_read_b128 v[184:187], v193 offset:18432
	ds_read_b128 v[196:199], v193 offset:19456
	ds_read_b128 v[200:203], v193 offset:20480
	ds_read_b128 v[204:207], v193 offset:21504
	ds_read_b128 v[218:221], v193 offset:22528
	ds_read_b128 v[222:225], v193 offset:23552
	global_load_lds_dwordx4 v[188:189], off
	s_add_i32 m0, s13, 0x2000
	s_add_u32 vcc_lo, s22, 0x40000
	v_lshl_add_u64 v[208:209], s[22:23], 0, v[14:15]
	s_addc_u32 vcc_hi, s23, 0
	s_add_i32 s12, s12, s5
	global_load_lds_dwordx4 v[208:209], off
	v_lshl_add_u64 v[210:211], vcc, 0, v[168:169]
	s_mov_b32 m0, s12
	v_lshl_add_u64 v[212:213], s[24:25], 0, v[166:167]
	global_load_lds_dwordx4 v[210:211], off
	v_lshl_add_u64 v[210:211], vcc, 0, v[14:15]
	s_add_i32 m0, s12, 0x2000
	s_nop 0
	global_load_lds_dwordx4 v[210:211], off
	v_lshl_add_u64 v[210:211], s[24:25], 0, v[170:171]
	s_mov_b32 m0, s10
	s_nop 0
	global_load_lds_dwordx4 v[210:211], off
	s_mov_b32 m0, s11
	s_nop 0
	global_load_lds_dwordx4 v[212:213], off
	s_waitcnt vmcnt(8)
	s_waitcnt lgkmcnt(0)
	s_barrier
; #define PG8_STAGE(bufoff, gbase, voff) do { _Pragma("unroll") for (int _i = 0; _i < 2; ++_i) \
;         __builtin_amdgcn_global_load_lds((const unsigned*)((const char*)(gbase) + (voff)[_i]), (PG8_LAS unsigned*)(lds + (bufoff) + ldsw + _i * 8192), 16, 0, 0); } while (0)
; #define PG8_LDA(dst, b, h) do { _Pragma("unroll") for (int m = 0; m < 4; ++m) _Pragma("unroll") for (int k = 0; k < 2; ++k) dst[m][k] = *(const PG8_LAS bf16x8*)(lds + PG8_SA(b, h) + aoff + m * 2048 + k * 1024); } while (0)
; #define PG8_LDB(dst, b, h) do { _Pragma("unroll") for (int n = 0; n < 2; ++n) _Pragma("unroll") for (int k = 0; k < 2; ++k) dst[n][k] = *(const PG8_LAS bf16x8*)(lds + PG8_SB(b, h) + boff + n * 2048 + k * 1024); } while (0)
; #define PG8_MMA(ai, bj, At, Bt) do { __builtin_amdgcn_s_setprio(1); _Pragma("unroll") for (int m = 0; m < 4; ++m) _Pragma("unroll") for (int n = 0; n < 2; ++n) _Pragma("unroll") for (int k = 0; k < 2; ++k) \
;         acc[ai][bj][m][n] = __builtin_amdgcn_mfma_f32_16x16x32_f16(Bt[n][k], At[m][k], acc[ai][bj][m][n], 0, 0, 0); __builtin_amdgcn_s_setprio(0); } while (0)
; #define PG8_WAIT_V(n) asm volatile("s_waitcnt vmcnt(" #n ")" ::: "memory")
; #define PG8_WAIT_L(n) asm volatile("s_waitcnt lgkmcnt(" #n ")" ::: "memory")
; #define PG8_BAR __builtin_amdgcn_s_barrier()
; #define PG8_SCHED __builtin_amdgcn_sched_barrier(0)
; template <class Epi, class Sched, bool ALIGN_EPI = false, bool SP2 = false>
; __device__ __forceinline__ void gemm_phase(PG8_LAS unsigned char* lds, const Gemm g, const Sched& S, const Epi& E) {
;     ...
;             PG8_LDA(At, 0, 1); PG8_STAGE(PG8_SB(0, 0), b2, voffB); PG8_STAGE(PG8_SB(0, 1), b2 + hstep, voffB); PG8_STAGE(PG8_SA(0, 0), a2, voffA);
;             PG8_WAIT_V(8); PG8_WAIT_L(0); PG8_BAR; PG8_MMA(1, 0, At, B0); PG8_MMA(1, 1, At, B1); PG8_BAR; PG8_SCHED;
;             PG8_LDB(B0, 1, 0); PG8_LDB(B1, 1, 1); PG8_SCHED; PG8_LDA(At, 1, 0); PG8_STAGE(PG8_SA(0, 1), a2 + hstep, voffA);
;             PG8_WAIT_V(8); PG8_WAIT_L(0); PG8_BAR; PG8_MMA(0, 0, At, B0); PG8_MMA(0, 1, At, B1); PG8_BAR; PG8_SCHED;
	v_mfma_f32_16x16x32_f16 v[66:69], v[94:97], v[176:179], v[66:69]
	v_mfma_f32_16x16x32_f16 v[62:65], v[102:105], v[176:179], v[62:65]
	v_mfma_f32_16x16x32_f16 v[50:53], v[94:97], v[184:187], v[50:53]
	v_mfma_f32_16x16x32_f16 v[46:49], v[102:105], v[184:187], v[46:49]
	v_mfma_f32_16x16x32_f16 v[34:37], v[94:97], v[200:203], v[34:37]
	v_mfma_f32_16x16x32_f16 v[30:33], v[102:105], v[200:203], v[30:33]
	v_mfma_f32_16x16x32_f16 v[18:21], v[94:97], v[218:221], v[18:21]
	v_mfma_f32_16x16x32_f16 v[10:13], v[102:105], v[218:221], v[10:13]
	v_mfma_f32_16x16x32_f16 v[66:69], v[98:101], v[180:183], v[66:69]
	v_mfma_f32_16x16x32_f16 v[62:65], v[106:109], v[180:183], v[62:65]
	v_mfma_f32_16x16x32_f16 v[50:53], v[98:101], v[196:199], v[50:53]
	v_mfma_f32_16x16x32_f16 v[46:49], v[106:109], v[196:199], v[46:49]
	v_mfma_f32_16x16x32_f16 v[34:37], v[98:101], v[204:207], v[34:37]
	v_mfma_f32_16x16x32_f16 v[30:33], v[106:109], v[204:207], v[30:33]
	v_mfma_f32_16x16x32_f16 v[18:21], v[98:101], v[222:225], v[18:21]
	v_mfma_f32_16x16x32_f16 v[10:13], v[106:109], v[222:225], v[10:13]
	v_mfma_f32_16x16x32_f16 v[58:61], v[114:117], v[176:179], v[58:61]
	v_mfma_f32_16x16x32_f16 v[54:57], v[126:129], v[176:179], v[54:57]
	v_mfma_f32_16x16x32_f16 v[42:45], v[114:117], v[184:187], v[42:45]
	v_mfma_f32_16x16x32_f16 v[38:41], v[126:129], v[184:187], v[38:41]
	v_mfma_f32_16x16x32_f16 v[26:29], v[114:117], v[200:203], v[26:29]
	v_mfma_f32_16x16x32_f16 v[22:25], v[126:129], v[200:203], v[22:25]
	v_mfma_f32_16x16x32_f16 v[6:9], v[114:117], v[218:221], v[6:9]
	v_mfma_f32_16x16x32_f16 v[2:5], v[126:129], v[218:221], v[2:5]
	v_mfma_f32_16x16x32_f16 v[58:61], v[118:121], v[180:183], v[58:61]
	v_mfma_f32_16x16x32_f16 v[54:57], v[130:133], v[180:183], v[54:57]
	v_mfma_f32_16x16x32_f16 v[42:45], v[118:121], v[196:199], v[42:45]
	v_mfma_f32_16x16x32_f16 v[38:41], v[130:133], v[196:199], v[38:41]
	v_mfma_f32_16x16x32_f16 v[26:29], v[118:121], v[204:207], v[26:29]
	v_mfma_f32_16x16x32_f16 v[22:25], v[130:133], v[204:207], v[22:25]
	v_mfma_f32_16x16x32_f16 v[6:9], v[118:121], v[222:225], v[6:9]
	v_mfma_f32_16x16x32_f16 v[2:5], v[130:133], v[222:225], v[2:5]
	s_barrier
	s_add_i32 s12, 0, 0x18000
	s_add_i32 s13, 0, 0x1c000
	v_add_u32_e32 v106, s12, v191
	v_add_u32_e32 v130, s13, v191
	ds_read_b128 v[94:97], v106
	ds_read_b128 v[98:101], v106 offset:1024
	ds_read_b128 v[102:105], v106 offset:2048
	ds_read_b128 v[106:109], v106 offset:3072
	ds_read_b128 v[114:117], v130
	ds_read_b128 v[118:121], v130 offset:1024
	ds_read_b128 v[126:129], v130 offset:2048
	ds_read_b128 v[130:133], v130 offset:3072
	s_add_u32 s24, s24, 0x40000
	s_addc_u32 s25, s25, 0
	s_mov_b32 m0, s26
	v_lshl_add_u64 v[214:215], s[24:25], 0, v[170:171]
	ds_read_b128 v[176:179], v193 offset:32768
	ds_read_b128 v[180:183], v193 offset:33792
	ds_read_b128 v[184:187], v193 offset:34816
	ds_read_b128 v[196:199], v193 offset:35840
	ds_read_b128 v[200:203], v193 offset:36864
	ds_read_b128 v[204:207], v193 offset:37888
	ds_read_b128 v[218:221], v193 offset:38912
	ds_read_b128 v[222:225], v193 offset:39936
	global_load_lds_dwordx4 v[214:215], off
	v_lshl_add_u64 v[214:215], s[24:25], 0, v[166:167]
	s_mov_b32 m0, s27
	s_nop 0
	global_load_lds_dwordx4 v[214:215], off
	s_waitcnt vmcnt(8)
	s_waitcnt lgkmcnt(0)
	s_barrier
	v_mfma_f32_16x16x32_f16 v[162:165], v[94:97], v[176:179], v[162:165]
	v_mfma_f32_16x16x32_f16 v[158:161], v[102:105], v[176:179], v[158:161]
	v_mfma_f32_16x16x32_f16 v[146:149], v[94:97], v[184:187], v[146:149]
	v_mfma_f32_16x16x32_f16 v[142:145], v[102:105], v[184:187], v[142:145]
	v_mfma_f32_16x16x32_f16 v[122:125], v[94:97], v[200:203], v[122:125]
	v_mfma_f32_16x16x32_f16 v[110:113], v[102:105], v[200:203], v[110:113]
	v_mfma_f32_16x16x32_f16 v[82:85], v[94:97], v[218:221], v[82:85]
	v_mfma_f32_16x16x32_f16 v[78:81], v[102:105], v[218:221], v[78:81]
	v_mfma_f32_16x16x32_f16 v[162:165], v[98:101], v[180:183], v[162:165]
	v_mfma_f32_16x16x32_f16 v[158:161], v[106:109], v[180:183], v[158:161]
	v_mfma_f32_16x16x32_f16 v[146:149], v[98:101], v[196:199], v[146:149]
	v_mfma_f32_16x16x32_f16 v[142:145], v[106:109], v[196:199], v[142:145]
	v_mfma_f32_16x16x32_f16 v[122:125], v[98:101], v[204:207], v[122:125]
	v_mfma_f32_16x16x32_f16 v[110:113], v[106:109], v[204:207], v[110:113]
	v_mfma_f32_16x16x32_f16 v[82:85], v[98:101], v[222:225], v[82:85]
	v_mfma_f32_16x16x32_f16 v[78:81], v[106:109], v[222:225], v[78:81]
	v_mfma_f32_16x16x32_f16 v[154:157], v[114:117], v[176:179], v[154:157]
	v_mfma_f32_16x16x32_f16 v[150:153], v[126:129], v[176:179], v[150:153]
	v_mfma_f32_16x16x32_f16 v[138:141], v[114:117], v[184:187], v[138:141]
	v_mfma_f32_16x16x32_f16 v[134:137], v[126:129], v[184:187], v[134:137]
	v_mfma_f32_16x16x32_f16 v[90:93], v[114:117], v[200:203], v[90:93]
	v_mfma_f32_16x16x32_f16 v[86:89], v[126:129], v[200:203], v[86:89]
	v_mfma_f32_16x16x32_f16 v[74:77], v[114:117], v[218:221], v[74:77]
	v_mfma_f32_16x16x32_f16 v[70:73], v[126:129], v[218:221], v[70:73]
	v_mfma_f32_16x16x32_f16 v[154:157], v[118:121], v[180:183], v[154:157]
	v_mfma_f32_16x16x32_f16 v[150:153], v[130:133], v[180:183], v[150:153]
	v_mfma_f32_16x16x32_f16 v[138:141], v[118:121], v[196:199], v[138:141]
	v_mfma_f32_16x16x32_f16 v[134:137], v[130:133], v[196:199], v[134:137]
	v_mfma_f32_16x16x32_f16 v[90:93], v[118:121], v[204:207], v[90:93]
	v_mfma_f32_16x16x32_f16 v[86:89], v[130:133], v[204:207], v[86:89]
	v_mfma_f32_16x16x32_f16 v[74:77], v[118:121], v[222:225], v[74:77]
	v_mfma_f32_16x16x32_f16 v[70:73], v[130:133], v[222:225], v[70:73]
	s_barrier
; #define PG8_STAGE(bufoff, gbase, voff) do { _Pragma("unroll") for (int _i = 0; _i < 2; ++_i) \
;         __builtin_amdgcn_global_load_lds((const unsigned*)((const char*)(gbase) + (voff)[_i]), (PG8_LAS unsigned*)(lds + (bufoff) + ldsw + _i * 8192), 16, 0, 0); } while (0)
; #define PG8_LDA(dst, b, h) do { _Pragma("unroll") for (int m = 0; m < 4; ++m) _Pragma("unroll") for (int k = 0; k < 2; ++k) dst[m][k] = *(const PG8_LAS bf16x8*)(lds + PG8_SA(b, h) + aoff + m * 2048 + k * 1024); } while (0)
; #define PG8_WAIT_V(n) asm volatile("s_waitcnt vmcnt(" #n ")" ::: "memory")
; template <class Epi, class Sched, bool ALIGN_EPI = false, bool SP2 = false>
; __device__ __forceinline__ void gemm_phase(PG8_LAS unsigned char* lds, const Gemm g, const Sched& S, const Epi& E) {
;     ...
;             PG8_LDA(At, 1, 1); PG8_STAGE(PG8_SB(1, 0), b3, voffB); PG8_STAGE(PG8_SB(1, 1), b3 + hstep, voffB); PG8_STAGE(PG8_SA(1, 0), a3, voffA);
;             PG8_WAIT_V(8); PG8_WAIT_L(0); PG8_BAR; PG8_MMA(1, 0, At, B0); PG8_MMA(1, 1, At, B1); PG8_BAR; PG8_SCHED;
;             } else {
;             PG8_LDB(B0, 0, 0); PG8_SCHED; PG8_LDA(At, 0, 0); PG8_STAGE(PG8_SA(1, 1), a1 + hstep, voffA);
;             PG8_WAIT_L(8); PG8_BAR; PG8_WAIT_L(0); PG8_MMA(0, 0, At, B0); PG8_BAR; PG8_SCHED;
;             PG8_LDB(B1, 0, 1); PG8_STAGE(PG8_SB(0, 0), b2, voffB);
;             PG8_BAR; PG8_WAIT_L(0); PG8_MMA(0, 1, At, B1); PG8_BAR;
;             PG8_LDA(At, 0, 1); PG8_STAGE(PG8_SA(0, 0), a2, voffA);
;             PG8_BAR; PG8_WAIT_L(0); PG8_MMA(1, 0, At, B0); PG8_BAR; PG8_SCHED;
;             PG8_STAGE(PG8_SB(0, 1), b2 + hstep, voffB);
;             PG8_WAIT_V(6); PG8_BAR; PG8_MMA(1, 1, At, B1); PG8_BAR;
;             PG8_LDB(B0, 1, 0); PG8_SCHED; PG8_LDA(At, 1, 0); PG8_STAGE(PG8_SA(0, 1), a2 + hstep, voffA);
;             PG8_WAIT_L(8); PG8_BAR; PG8_WAIT_L(0); PG8_MMA(0, 0, At, B0); PG8_BAR; PG8_SCHED;
;             PG8_LDB(B1, 1, 1); PG8_STAGE(PG8_SB(1, 0), b3, voffB);
;             PG8_BAR; PG8_WAIT_L(0); PG8_MMA(0, 1, At, B1); PG8_BAR;
;             PG8_LDA(At, 1, 1); PG8_STAGE(PG8_SA(1, 0), a3, voffA);
;             PG8_BAR; PG8_WAIT_L(0); PG8_MMA(1, 0, At, B0); PG8_BAR; PG8_SCHED;
;             PG8_STAGE(PG8_SB(1, 1), b3 + hstep, voffB);
;             PG8_WAIT_V(6); PG8_BAR; PG8_MMA(1, 1, At, B1); PG8_BAR;
;             }
;         }
;         if constexpr (ALIGN_EPI) { if (wr == 0) PG8_BAR; }
	s_add_i32 s12, s12, s5
	v_lshl_add_u64 v[188:189], v[188:189], 0, s[34:35]
	s_mov_b32 m0, s12
	ds_read_b128 v[176:179], v193 offset:49152
	ds_read_b128 v[180:183], v193 offset:50176
	ds_read_b128 v[184:187], v193 offset:51200
	ds_read_b128 v[196:199], v193 offset:52224
	ds_read_b128 v[200:203], v193 offset:53248
	ds_read_b128 v[204:207], v193 offset:54272
	ds_read_b128 v[218:221], v193 offset:55296
	ds_read_b128 v[222:225], v193 offset:56320
	global_load_lds_dwordx4 v[188:189], off
	s_add_i32 m0, s12, 0x2000
	s_add_u32 s22, s22, 0x40080
	v_lshl_add_u64 v[188:189], v[208:209], 0, s[34:35]
	s_addc_u32 s23, s23, 0
	s_add_i32 s12, s13, s5
	global_load_lds_dwordx4 v[188:189], off
	v_lshl_add_u64 v[188:189], s[22:23], 0, v[168:169]
	s_mov_b32 m0, s12
	s_nop 0
	global_load_lds_dwordx4 v[188:189], off
	v_lshl_add_u64 v[188:189], s[22:23], 0, v[14:15]
	s_add_i32 m0, s12, 0x2000
	s_nop 0
	global_load_lds_dwordx4 v[188:189], off
	v_lshl_add_u64 v[188:189], v[210:211], 0, s[34:35]
	s_mov_b32 m0, s49
	s_nop 0
	global_load_lds_dwordx4 v[188:189], off
	v_lshl_add_u64 v[188:189], v[212:213], 0, s[34:35]
	s_mov_b32 m0, s58
	s_nop 0
	global_load_lds_dwordx4 v[188:189], off
	s_waitcnt vmcnt(8)
	s_waitcnt lgkmcnt(0)
	s_barrier
	v_mfma_f32_16x16x32_f16 v[66:69], v[94:97], v[176:179], v[66:69]
	v_mfma_f32_16x16x32_f16 v[62:65], v[102:105], v[176:179], v[62:65]
	v_mfma_f32_16x16x32_f16 v[50:53], v[94:97], v[184:187], v[50:53]
	v_mfma_f32_16x16x32_f16 v[46:49], v[102:105], v[184:187], v[46:49]
	v_mfma_f32_16x16x32_f16 v[34:37], v[94:97], v[200:203], v[34:37]
	v_mfma_f32_16x16x32_f16 v[30:33], v[102:105], v[200:203], v[30:33]
	v_mfma_f32_16x16x32_f16 v[18:21], v[94:97], v[218:221], v[18:21]
	v_mfma_f32_16x16x32_f16 v[10:13], v[102:105], v[218:221], v[10:13]
	v_mfma_f32_16x16x32_f16 v[66:69], v[98:101], v[180:183], v[66:69]
	v_mfma_f32_16x16x32_f16 v[62:65], v[106:109], v[180:183], v[62:65]
	v_mfma_f32_16x16x32_f16 v[50:53], v[98:101], v[196:199], v[50:53]
	v_mfma_f32_16x16x32_f16 v[46:49], v[106:109], v[196:199], v[46:49]
	v_mfma_f32_16x16x32_f16 v[34:37], v[98:101], v[204:207], v[34:37]
	v_mfma_f32_16x16x32_f16 v[30:33], v[106:109], v[204:207], v[30:33]
	v_mfma_f32_16x16x32_f16 v[18:21], v[98:101], v[222:225], v[18:21]
	v_mfma_f32_16x16x32_f16 v[10:13], v[106:109], v[222:225], v[10:13]
	v_mfma_f32_16x16x32_f16 v[58:61], v[114:117], v[176:179], v[58:61]
	v_mfma_f32_16x16x32_f16 v[54:57], v[126:129], v[176:179], v[54:57]
	v_mfma_f32_16x16x32_f16 v[42:45], v[114:117], v[184:187], v[42:45]
	v_mfma_f32_16x16x32_f16 v[38:41], v[126:129], v[184:187], v[38:41]
	v_mfma_f32_16x16x32_f16 v[26:29], v[114:117], v[200:203], v[26:29]
	v_mfma_f32_16x16x32_f16 v[22:25], v[126:129], v[200:203], v[22:25]
	v_mfma_f32_16x16x32_f16 v[6:9], v[114:117], v[218:221], v[6:9]
	v_mfma_f32_16x16x32_f16 v[2:5], v[126:129], v[218:221], v[2:5]
	v_mfma_f32_16x16x32_f16 v[58:61], v[118:121], v[180:183], v[58:61]
	v_mfma_f32_16x16x32_f16 v[54:57], v[130:133], v[180:183], v[54:57]
	v_mfma_f32_16x16x32_f16 v[42:45], v[118:121], v[196:199], v[42:45]
	v_mfma_f32_16x16x32_f16 v[38:41], v[130:133], v[196:199], v[38:41]
	v_mfma_f32_16x16x32_f16 v[26:29], v[118:121], v[204:207], v[26:29]
	v_mfma_f32_16x16x32_f16 v[22:25], v[130:133], v[204:207], v[22:25]
	v_mfma_f32_16x16x32_f16 v[6:9], v[118:121], v[222:225], v[6:9]
	v_mfma_f32_16x16x32_f16 v[2:5], v[130:133], v[222:225], v[2:5]
	s_barrier
	s_add_i32 s83, s83, 2
	s_add_u32 s50, s50, 0x100
	s_addc_u32 s51, s51, 0
	s_add_u32 s77, s77, 0x100
	s_addc_u32 s82, s82, 0
	s_cmp_gt_u32 s83, 13
	s_cbranch_scc0 .LBB0_185
	s_and_b64 vcc, exec, s[14:15]
	s_cbranch_vccz .LBB0_188
	s_barrier

; #define PG8_STAGE(bufoff, gbase, voff) do { _Pragma("unroll") for (int _i = 0; _i < 2; ++_i) \
;         __builtin_amdgcn_global_load_lds((const unsigned*)((const char*)(gbase) + (voff)[_i]), (PG8_LAS unsigned*)(lds + (bufoff) + ldsw + _i * 8192), 16, 0, 0); } while (0)
; #define PG8_LDA(dst, b, h) do { _Pragma("unroll") for (int m = 0; m < 4; ++m) _Pragma("unroll") for (int k = 0; k < 2; ++k) dst[m][k] = *(const PG8_LAS bf16x8*)(lds + PG8_SA(b, h) + aoff + m * 2048 + k * 1024); } while (0)
; #define PG8_LDB(dst, b, h) do { _Pragma("unroll") for (int n = 0; n < 2; ++n) _Pragma("unroll") for (int k = 0; k < 2; ++k) dst[n][k] = *(const PG8_LAS bf16x8*)(lds + PG8_SB(b, h) + boff + n * 2048 + k * 1024); } while (0)
; #define PG8_MMA(ai, bj, At, Bt) do { __builtin_amdgcn_s_setprio(1); _Pragma("unroll") for (int m = 0; m < 4; ++m) _Pragma("unroll") for (int n = 0; n < 2; ++n) _Pragma("unroll") for (int k = 0; k < 2; ++k) \
;         acc[ai][bj][m][n] = __builtin_amdgcn_mfma_f32_16x16x32_f16(Bt[n][k], At[m][k], acc[ai][bj][m][n], 0, 0, 0); __builtin_amdgcn_s_setprio(0); } while (0)
; #define PG8_WAIT_V(n) asm volatile("s_waitcnt vmcnt(" #n ")" ::: "memory")
; #define PG8_WAIT_L(n) asm volatile("s_waitcnt lgkmcnt(" #n ")" ::: "memory")
; #define PG8_BAR __builtin_amdgcn_s_barrier()
; #define PG8_SCHED __builtin_amdgcn_sched_barrier(0)
; template <class Epi, class Sched, bool ALIGN_EPI = false, bool SP2 = false>
; __device__ __forceinline__ void gemm_phase(PG8_LAS unsigned char* lds, const Gemm g, const Sched& S, const Epi& E) {
;     ...
;         for (int t = 0; t < nt; t += 2) {
;             const bool last = (t == nt - 2);
;             const char* a1 = cA + (size_t)(t + 1) * kstep;
;             const char* a2 = last ? nA : cA + (size_t)(t + 2) * kstep; const char* b2 = last ? nB : cB + (size_t)(t + 2) * kstep;
;             const char* a3 = a2 + kstep; const char* b3 = b2 + kstep;
;             if (last && has_next) S.a_ready(nxt);
;             if constexpr (SP2) {
;             PG8_LDB(B0, 0, 0); PG8_LDB(B1, 0, 1); PG8_SCHED; PG8_LDA(At, 0, 0); PG8_STAGE(PG8_SA(1, 1), a1 + hstep, voffA);
;             PG8_WAIT_V(8); PG8_WAIT_L(0); PG8_BAR; PG8_MMA(0, 0, At, B0); PG8_MMA(0, 1, At, B1); PG8_BAR; PG8_SCHED;
;             PG8_LDA(At, 0, 1); PG8_STAGE(PG8_SB(0, 0), b2, voffB); PG8_STAGE(PG8_SB(0, 1), b2 + hstep, voffB); PG8_STAGE(PG8_SA(0, 0), a2, voffA);
.LBB0_269:
	s_add_u32 s12, s50, 0xfffc0080
	s_addc_u32 s13, s51, -1
	s_add_i32 s83, 0, 0x10000
	s_cmp_eq_u32 s82, 12
	s_cselect_b32 s25, s39, s13
	s_cselect_b32 s24, s72, s12
	v_add_u32_e32 v152, s83, v154
	s_cselect_b32 s23, s17, s77
	s_cselect_b32 s22, s73, s76
	s_add_i32 s12, 0, 0x14000
	ds_read_b128 v[144:147], v152
	ds_read_b128 v[148:151], v152 offset:1024
	ds_read_b128 v[156:159], v152 offset:2048
	ds_read_b128 v[160:163], v152 offset:3072
	v_add_u32_e32 v152, s12, v154
	ds_read_b128 v[164:167], v152
	ds_read_b128 v[168:171], v152 offset:1024
	ds_read_b128 v[172:175], v152 offset:2048
	ds_read_b128 v[176:179], v152 offset:3072
	v_lshl_add_u64 v[152:153], s[50:51], 0, v[140:141]
	s_add_i32 m0, s10, 0xc000
	ds_read_b128 v[180:183], v155
	ds_read_b128 v[184:187], v155 offset:1024
	ds_read_b128 v[188:191], v155 offset:2048
	ds_read_b128 v[192:195], v155 offset:3072
	ds_read_b128 v[196:199], v155 offset:4096
	ds_read_b128 v[200:203], v155 offset:5120
	ds_read_b128 v[204:207], v155 offset:6144
	ds_read_b128 v[218:221], v155 offset:7168
	global_load_lds_dwordx4 v[152:153], off
	v_lshl_add_u64 v[152:153], s[50:51], 0, v[142:143]
	s_add_i32 m0, s10, 0xe000
	s_nop 0
	global_load_lds_dwordx4 v[152:153], off
	s_waitcnt vmcnt(8)
	s_waitcnt lgkmcnt(0)
	s_barrier
	v_mfma_f32_16x16x32_f16 v[130:133], v[144:147], v[180:183], v[130:133]
	v_mfma_f32_16x16x32_f16 v[126:129], v[156:159], v[180:183], v[126:129]
	v_mfma_f32_16x16x32_f16 v[114:117], v[144:147], v[188:191], v[114:117]
	v_mfma_f32_16x16x32_f16 v[110:113], v[156:159], v[188:191], v[110:113]
	v_mfma_f32_16x16x32_f16 v[98:101], v[144:147], v[196:199], v[98:101]
	v_mfma_f32_16x16x32_f16 v[94:97], v[156:159], v[196:199], v[94:97]
	v_mfma_f32_16x16x32_f16 v[82:85], v[144:147], v[204:207], v[82:85]
	v_mfma_f32_16x16x32_f16 v[78:81], v[156:159], v[204:207], v[78:81]
	v_mfma_f32_16x16x32_f16 v[130:133], v[148:151], v[184:187], v[130:133]
	v_mfma_f32_16x16x32_f16 v[126:129], v[160:163], v[184:187], v[126:129]
	v_mfma_f32_16x16x32_f16 v[114:117], v[148:151], v[192:195], v[114:117]
	v_mfma_f32_16x16x32_f16 v[110:113], v[160:163], v[192:195], v[110:113]
	v_mfma_f32_16x16x32_f16 v[98:101], v[148:151], v[200:203], v[98:101]
	v_mfma_f32_16x16x32_f16 v[94:97], v[160:163], v[200:203], v[94:97]
	v_mfma_f32_16x16x32_f16 v[82:85], v[148:151], v[218:221], v[82:85]
	v_mfma_f32_16x16x32_f16 v[78:81], v[160:163], v[218:221], v[78:81]
	v_mfma_f32_16x16x32_f16 v[122:125], v[164:167], v[180:183], v[122:125]
	v_mfma_f32_16x16x32_f16 v[118:121], v[172:175], v[180:183], v[118:121]
	v_mfma_f32_16x16x32_f16 v[106:109], v[164:167], v[188:191], v[106:109]
	v_mfma_f32_16x16x32_f16 v[102:105], v[172:175], v[188:191], v[102:105]
	v_mfma_f32_16x16x32_f16 v[90:93], v[164:167], v[196:199], v[90:93]
	v_mfma_f32_16x16x32_f16 v[86:89], v[172:175], v[196:199], v[86:89]
	v_mfma_f32_16x16x32_f16 v[74:77], v[164:167], v[204:207], v[74:77]
	v_mfma_f32_16x16x32_f16 v[70:73], v[172:175], v[204:207], v[70:73]
	v_mfma_f32_16x16x32_f16 v[122:125], v[168:171], v[184:187], v[122:125]
	v_mfma_f32_16x16x32_f16 v[118:121], v[176:179], v[184:187], v[118:121]
	v_mfma_f32_16x16x32_f16 v[106:109], v[168:171], v[192:195], v[106:109]
	v_mfma_f32_16x16x32_f16 v[102:105], v[176:179], v[192:195], v[102:105]
	v_mfma_f32_16x16x32_f16 v[90:93], v[168:171], v[200:203], v[90:93]
	v_mfma_f32_16x16x32_f16 v[86:89], v[176:179], v[200:203], v[86:89]
	v_mfma_f32_16x16x32_f16 v[74:77], v[168:171], v[218:221], v[74:77]
	v_mfma_f32_16x16x32_f16 v[70:73], v[176:179], v[218:221], v[70:73]
	s_barrier
	s_add_i32 s13, s83, s5
	v_lshl_add_u64 v[152:153], s[22:23], 0, v[136:137]
	s_mov_b32 m0, s13
	ds_read_b128 v[180:183], v155 offset:16384
	ds_read_b128 v[184:187], v155 offset:17408
	ds_read_b128 v[188:191], v155 offset:18432
	ds_read_b128 v[192:195], v155 offset:19456
	ds_read_b128 v[196:199], v155 offset:20480
	ds_read_b128 v[200:203], v155 offset:21504
	ds_read_b128 v[204:207], v155 offset:22528
	ds_read_b128 v[218:221], v155 offset:23552
	global_load_lds_dwordx4 v[152:153], off
	s_add_i32 m0, s13, 0x2000
	s_add_u32 vcc_lo, s22, 0x40000
	v_lshl_add_u64 v[208:209], s[22:23], 0, v[14:15]
	s_addc_u32 vcc_hi, s23, 0
	s_add_i32 s12, s12, s5
	global_load_lds_dwordx4 v[208:209], off
	v_lshl_add_u64 v[210:211], vcc, 0, v[136:137]
	s_mov_b32 m0, s12
	v_lshl_add_u64 v[212:213], s[24:25], 0, v[134:135]
	global_load_lds_dwordx4 v[210:211], off
	v_lshl_add_u64 v[210:211], vcc, 0, v[14:15]
	s_add_i32 m0, s12, 0x2000
	s_nop 0
	global_load_lds_dwordx4 v[210:211], off
	v_lshl_add_u64 v[210:211], s[24:25], 0, v[138:139]
	s_mov_b32 m0, s10
	s_nop 0
	global_load_lds_dwordx4 v[210:211], off
	s_mov_b32 m0, s11
	s_nop 0
	global_load_lds_dwordx4 v[212:213], off
	s_waitcnt vmcnt(8)
	s_waitcnt lgkmcnt(0)
	s_barrier
; #define PG8_STAGE(bufoff, gbase, voff) do { _Pragma("unroll") for (int _i = 0; _i < 2; ++_i) \
;         __builtin_amdgcn_global_load_lds((const unsigned*)((const char*)(gbase) + (voff)[_i]), (PG8_LAS unsigned*)(lds + (bufoff) + ldsw + _i * 8192), 16, 0, 0); } while (0)
; #define PG8_LDA(dst, b, h) do { _Pragma("unroll") for (int m = 0; m < 4; ++m) _Pragma("unroll") for (int k = 0; k < 2; ++k) dst[m][k] = *(const PG8_LAS bf16x8*)(lds + PG8_SA(b, h) + aoff + m * 2048 + k * 1024); } while (0)
; #define PG8_LDB(dst, b, h) do { _Pragma("unroll") for (int n = 0; n < 2; ++n) _Pragma("unroll") for (int k = 0; k < 2; ++k) dst[n][k] = *(const PG8_LAS bf16x8*)(lds + PG8_SB(b, h) + boff + n * 2048 + k * 1024); } while (0)
; #define PG8_MMA(ai, bj, At, Bt) do { __builtin_amdgcn_s_setprio(1); _Pragma("unroll") for (int m = 0; m < 4; ++m) _Pragma("unroll") for (int n = 0; n < 2; ++n) _Pragma("unroll") for (int k = 0; k < 2; ++k) \
;         acc[ai][bj][m][n] = __builtin_amdgcn_mfma_f32_16x16x32_f16(Bt[n][k], At[m][k], acc[ai][bj][m][n], 0, 0, 0); __builtin_amdgcn_s_setprio(0); } while (0)
; #define PG8_WAIT_V(n) asm volatile("s_waitcnt vmcnt(" #n ")" ::: "memory")
; #define PG8_WAIT_L(n) asm volatile("s_waitcnt lgkmcnt(" #n ")" ::: "memory")
; #define PG8_BAR __builtin_amdgcn_s_barrier()
; #define PG8_SCHED __builtin_amdgcn_sched_barrier(0)
; template <class Epi, class Sched, bool ALIGN_EPI = false, bool SP2 = false>
; __device__ __forceinline__ void gemm_phase(PG8_LAS unsigned char* lds, const Gemm g, const Sched& S, const Epi& E) {
;     ...
;             PG8_LDA(At, 0, 1); PG8_STAGE(PG8_SB(0, 0), b2, voffB); PG8_STAGE(PG8_SB(0, 1), b2 + hstep, voffB); PG8_STAGE(PG8_SA(0, 0), a2, voffA);
;             PG8_WAIT_V(8); PG8_WAIT_L(0); PG8_BAR; PG8_MMA(1, 0, At, B0); PG8_MMA(1, 1, At, B1); PG8_BAR; PG8_SCHED;
;             PG8_LDB(B0, 1, 0); PG8_LDB(B1, 1, 1); PG8_SCHED; PG8_LDA(At, 1, 0); PG8_STAGE(PG8_SA(0, 1), a2 + hstep, voffA);
;             PG8_WAIT_V(8); PG8_WAIT_L(0); PG8_BAR; PG8_MMA(0, 0, At, B0); PG8_MMA(0, 1, At, B1); PG8_BAR; PG8_SCHED;
	v_mfma_f32_16x16x32_f16 v[66:69], v[144:147], v[180:183], v[66:69]
	v_mfma_f32_16x16x32_f16 v[62:65], v[156:159], v[180:183], v[62:65]
	v_mfma_f32_16x16x32_f16 v[50:53], v[144:147], v[188:191], v[50:53]
	v_mfma_f32_16x16x32_f16 v[46:49], v[156:159], v[188:191], v[46:49]
	v_mfma_f32_16x16x32_f16 v[34:37], v[144:147], v[196:199], v[34:37]
	v_mfma_f32_16x16x32_f16 v[30:33], v[156:159], v[196:199], v[30:33]
	v_mfma_f32_16x16x32_f16 v[18:21], v[144:147], v[204:207], v[18:21]
	v_mfma_f32_16x16x32_f16 v[10:13], v[156:159], v[204:207], v[10:13]
	v_mfma_f32_16x16x32_f16 v[66:69], v[148:151], v[184:187], v[66:69]
	v_mfma_f32_16x16x32_f16 v[62:65], v[160:163], v[184:187], v[62:65]
	v_mfma_f32_16x16x32_f16 v[50:53], v[148:151], v[192:195], v[50:53]
	v_mfma_f32_16x16x32_f16 v[46:49], v[160:163], v[192:195], v[46:49]
	v_mfma_f32_16x16x32_f16 v[34:37], v[148:151], v[200:203], v[34:37]
	v_mfma_f32_16x16x32_f16 v[30:33], v[160:163], v[200:203], v[30:33]
	v_mfma_f32_16x16x32_f16 v[18:21], v[148:151], v[218:221], v[18:21]
	v_mfma_f32_16x16x32_f16 v[10:13], v[160:163], v[218:221], v[10:13]
	v_mfma_f32_16x16x32_f16 v[58:61], v[164:167], v[180:183], v[58:61]
	v_mfma_f32_16x16x32_f16 v[54:57], v[172:175], v[180:183], v[54:57]
	v_mfma_f32_16x16x32_f16 v[42:45], v[164:167], v[188:191], v[42:45]
	v_mfma_f32_16x16x32_f16 v[38:41], v[172:175], v[188:191], v[38:41]
	v_mfma_f32_16x16x32_f16 v[26:29], v[164:167], v[196:199], v[26:29]
	v_mfma_f32_16x16x32_f16 v[22:25], v[172:175], v[196:199], v[22:25]
	v_mfma_f32_16x16x32_f16 v[6:9], v[164:167], v[204:207], v[6:9]
	v_mfma_f32_16x16x32_f16 v[2:5], v[172:175], v[204:207], v[2:5]
	v_mfma_f32_16x16x32_f16 v[58:61], v[168:171], v[184:187], v[58:61]
	v_mfma_f32_16x16x32_f16 v[54:57], v[176:179], v[184:187], v[54:57]
	v_mfma_f32_16x16x32_f16 v[42:45], v[168:171], v[192:195], v[42:45]
	v_mfma_f32_16x16x32_f16 v[38:41], v[176:179], v[192:195], v[38:41]
	v_mfma_f32_16x16x32_f16 v[26:29], v[168:171], v[200:203], v[26:29]
	v_mfma_f32_16x16x32_f16 v[22:25], v[176:179], v[200:203], v[22:25]
	v_mfma_f32_16x16x32_f16 v[6:9], v[168:171], v[218:221], v[6:9]
	v_mfma_f32_16x16x32_f16 v[2:5], v[176:179], v[218:221], v[2:5]
	s_barrier
	s_add_i32 s12, 0, 0x18000
	s_add_i32 s13, 0, 0x1c000
	v_add_u32_e32 v160, s12, v154
	v_add_u32_e32 v176, s13, v154
	ds_read_b128 v[144:147], v160
	ds_read_b128 v[148:151], v160 offset:1024
	ds_read_b128 v[156:159], v160 offset:2048
	ds_read_b128 v[160:163], v160 offset:3072
	ds_read_b128 v[164:167], v176
	ds_read_b128 v[168:171], v176 offset:1024
	ds_read_b128 v[172:175], v176 offset:2048
	ds_read_b128 v[176:179], v176 offset:3072
	s_add_u32 s24, s24, 0x40000
	s_addc_u32 s25, s25, 0
	s_mov_b32 m0, s20
	v_lshl_add_u64 v[214:215], s[24:25], 0, v[138:139]
	ds_read_b128 v[180:183], v155 offset:32768
	ds_read_b128 v[184:187], v155 offset:33792
	ds_read_b128 v[188:191], v155 offset:34816
	ds_read_b128 v[192:195], v155 offset:35840
	ds_read_b128 v[196:199], v155 offset:36864
	ds_read_b128 v[200:203], v155 offset:37888
	ds_read_b128 v[204:207], v155 offset:38912
	ds_read_b128 v[218:221], v155 offset:39936
	global_load_lds_dwordx4 v[214:215], off
	v_lshl_add_u64 v[214:215], s[24:25], 0, v[134:135]
	s_mov_b32 m0, s26
	s_nop 0
	global_load_lds_dwordx4 v[214:215], off
	s_waitcnt vmcnt(8)
	s_waitcnt lgkmcnt(0)
	s_barrier
	v_mfma_f32_16x16x32_f16 v[130:133], v[144:147], v[180:183], v[130:133]
	v_mfma_f32_16x16x32_f16 v[126:129], v[156:159], v[180:183], v[126:129]
	v_mfma_f32_16x16x32_f16 v[114:117], v[144:147], v[188:191], v[114:117]
	v_mfma_f32_16x16x32_f16 v[110:113], v[156:159], v[188:191], v[110:113]
	v_mfma_f32_16x16x32_f16 v[98:101], v[144:147], v[196:199], v[98:101]
	v_mfma_f32_16x16x32_f16 v[94:97], v[156:159], v[196:199], v[94:97]
	v_mfma_f32_16x16x32_f16 v[82:85], v[144:147], v[204:207], v[82:85]
	v_mfma_f32_16x16x32_f16 v[78:81], v[156:159], v[204:207], v[78:81]
	v_mfma_f32_16x16x32_f16 v[130:133], v[148:151], v[184:187], v[130:133]
	v_mfma_f32_16x16x32_f16 v[126:129], v[160:163], v[184:187], v[126:129]
	v_mfma_f32_16x16x32_f16 v[114:117], v[148:151], v[192:195], v[114:117]
	v_mfma_f32_16x16x32_f16 v[110:113], v[160:163], v[192:195], v[110:113]
	v_mfma_f32_16x16x32_f16 v[98:101], v[148:151], v[200:203], v[98:101]
	v_mfma_f32_16x16x32_f16 v[94:97], v[160:163], v[200:203], v[94:97]
	v_mfma_f32_16x16x32_f16 v[82:85], v[148:151], v[218:221], v[82:85]
	v_mfma_f32_16x16x32_f16 v[78:81], v[160:163], v[218:221], v[78:81]
	v_mfma_f32_16x16x32_f16 v[122:125], v[164:167], v[180:183], v[122:125]
	v_mfma_f32_16x16x32_f16 v[118:121], v[172:175], v[180:183], v[118:121]
	v_mfma_f32_16x16x32_f16 v[106:109], v[164:167], v[188:191], v[106:109]
	v_mfma_f32_16x16x32_f16 v[102:105], v[172:175], v[188:191], v[102:105]
	v_mfma_f32_16x16x32_f16 v[90:93], v[164:167], v[196:199], v[90:93]
	v_mfma_f32_16x16x32_f16 v[86:89], v[172:175], v[196:199], v[86:89]
	v_mfma_f32_16x16x32_f16 v[74:77], v[164:167], v[204:207], v[74:77]
	v_mfma_f32_16x16x32_f16 v[70:73], v[172:175], v[204:207], v[70:73]
	v_mfma_f32_16x16x32_f16 v[122:125], v[168:171], v[184:187], v[122:125]
	v_mfma_f32_16x16x32_f16 v[118:121], v[176:179], v[184:187], v[118:121]
	v_mfma_f32_16x16x32_f16 v[106:109], v[168:171], v[192:195], v[106:109]
	v_mfma_f32_16x16x32_f16 v[102:105], v[176:179], v[192:195], v[102:105]
	v_mfma_f32_16x16x32_f16 v[90:93], v[168:171], v[200:203], v[90:93]
	v_mfma_f32_16x16x32_f16 v[86:89], v[176:179], v[200:203], v[86:89]
	v_mfma_f32_16x16x32_f16 v[74:77], v[168:171], v[218:221], v[74:77]
	v_mfma_f32_16x16x32_f16 v[70:73], v[176:179], v[218:221], v[70:73]
	s_barrier
; #define PG8_STAGE(bufoff, gbase, voff) do { _Pragma("unroll") for (int _i = 0; _i < 2; ++_i) \
;         __builtin_amdgcn_global_load_lds((const unsigned*)((const char*)(gbase) + (voff)[_i]), (PG8_LAS unsigned*)(lds + (bufoff) + ldsw + _i * 8192), 16, 0, 0); } while (0)
; #define PG8_LDA(dst, b, h) do { _Pragma("unroll") for (int m = 0; m < 4; ++m) _Pragma("unroll") for (int k = 0; k < 2; ++k) dst[m][k] = *(const PG8_LAS bf16x8*)(lds + PG8_SA(b, h) + aoff + m * 2048 + k * 1024); } while (0)
; #define PG8_WAIT_V(n) asm volatile("s_waitcnt vmcnt(" #n ")" ::: "memory")
; template <class Epi, class Sched, bool ALIGN_EPI = false, bool SP2 = false>
; __device__ __forceinline__ void gemm_phase(PG8_LAS unsigned char* lds, const Gemm g, const Sched& S, const Epi& E) {
;     ...
;             PG8_LDA(At, 1, 1); PG8_STAGE(PG8_SB(1, 0), b3, voffB); PG8_STAGE(PG8_SB(1, 1), b3 + hstep, voffB); PG8_STAGE(PG8_SA(1, 0), a3, voffA);
;             PG8_WAIT_V(8); PG8_WAIT_L(0); PG8_BAR; PG8_MMA(1, 0, At, B0); PG8_MMA(1, 1, At, B1); PG8_BAR; PG8_SCHED;
;             } else {
;             PG8_LDB(B0, 0, 0); PG8_SCHED; PG8_LDA(At, 0, 0); PG8_STAGE(PG8_SA(1, 1), a1 + hstep, voffA);
;             PG8_WAIT_L(8); PG8_BAR; PG8_WAIT_L(0); PG8_MMA(0, 0, At, B0); PG8_BAR; PG8_SCHED;
;             PG8_LDB(B1, 0, 1); PG8_STAGE(PG8_SB(0, 0), b2, voffB);
;             PG8_BAR; PG8_WAIT_L(0); PG8_MMA(0, 1, At, B1); PG8_BAR;
;             PG8_LDA(At, 0, 1); PG8_STAGE(PG8_SA(0, 0), a2, voffA);
;             PG8_BAR; PG8_WAIT_L(0); PG8_MMA(1, 0, At, B0); PG8_BAR; PG8_SCHED;
;             PG8_STAGE(PG8_SB(0, 1), b2 + hstep, voffB);
;             PG8_WAIT_V(6); PG8_BAR; PG8_MMA(1, 1, At, B1); PG8_BAR;
;             PG8_LDB(B0, 1, 0); PG8_SCHED; PG8_LDA(At, 1, 0); PG8_STAGE(PG8_SA(0, 1), a2 + hstep, voffA);
;             PG8_WAIT_L(8); PG8_BAR; PG8_WAIT_L(0); PG8_MMA(0, 0, At, B0); PG8_BAR; PG8_SCHED;
;             PG8_LDB(B1, 1, 1); PG8_STAGE(PG8_SB(1, 0), b3, voffB);
;             PG8_BAR; PG8_WAIT_L(0); PG8_MMA(0, 1, At, B1); PG8_BAR;
;             PG8_LDA(At, 1, 1); PG8_STAGE(PG8_SA(1, 0), a3, voffA);
;             PG8_BAR; PG8_WAIT_L(0); PG8_MMA(1, 0, At, B0); PG8_BAR; PG8_SCHED;
;             PG8_STAGE(PG8_SB(1, 1), b3 + hstep, voffB);
;             PG8_WAIT_V(6); PG8_BAR; PG8_MMA(1, 1, At, B1); PG8_BAR;
;             }
;         }
;         if constexpr (ALIGN_EPI) { if (wr == 0) PG8_BAR; }
	s_add_i32 s12, s12, s5
	v_lshl_add_u64 v[152:153], v[152:153], 0, s[34:35]
	s_mov_b32 m0, s12
	ds_read_b128 v[180:183], v155 offset:49152
	ds_read_b128 v[184:187], v155 offset:50176
	ds_read_b128 v[188:191], v155 offset:51200
	ds_read_b128 v[192:195], v155 offset:52224
	ds_read_b128 v[196:199], v155 offset:53248
	ds_read_b128 v[200:203], v155 offset:54272
	ds_read_b128 v[204:207], v155 offset:55296
	ds_read_b128 v[218:221], v155 offset:56320
	global_load_lds_dwordx4 v[152:153], off
	s_add_i32 m0, s12, 0x2000
	s_add_u32 s22, s22, 0x40080
	v_lshl_add_u64 v[152:153], v[208:209], 0, s[34:35]
	s_addc_u32 s23, s23, 0
	s_add_i32 s12, s13, s5
	global_load_lds_dwordx4 v[152:153], off
	v_lshl_add_u64 v[152:153], s[22:23], 0, v[136:137]
	s_mov_b32 m0, s12
	s_nop 0
	global_load_lds_dwordx4 v[152:153], off
	v_lshl_add_u64 v[152:153], s[22:23], 0, v[14:15]
	s_add_i32 m0, s12, 0x2000
	s_nop 0
	global_load_lds_dwordx4 v[152:153], off
	v_lshl_add_u64 v[152:153], v[210:211], 0, s[34:35]
	s_mov_b32 m0, s29
	s_nop 0
	global_load_lds_dwordx4 v[152:153], off
	v_lshl_add_u64 v[152:153], v[212:213], 0, s[34:35]
	s_mov_b32 m0, s33
	s_nop 0
	global_load_lds_dwordx4 v[152:153], off
	s_waitcnt vmcnt(8)
	s_waitcnt lgkmcnt(0)
	s_barrier
	v_mfma_f32_16x16x32_f16 v[66:69], v[144:147], v[180:183], v[66:69]
	v_mfma_f32_16x16x32_f16 v[62:65], v[156:159], v[180:183], v[62:65]
	v_mfma_f32_16x16x32_f16 v[50:53], v[144:147], v[188:191], v[50:53]
	v_mfma_f32_16x16x32_f16 v[46:49], v[156:159], v[188:191], v[46:49]
	v_mfma_f32_16x16x32_f16 v[34:37], v[144:147], v[196:199], v[34:37]
	v_mfma_f32_16x16x32_f16 v[30:33], v[156:159], v[196:199], v[30:33]
	v_mfma_f32_16x16x32_f16 v[18:21], v[144:147], v[204:207], v[18:21]
	v_mfma_f32_16x16x32_f16 v[10:13], v[156:159], v[204:207], v[10:13]
	v_mfma_f32_16x16x32_f16 v[66:69], v[148:151], v[184:187], v[66:69]
	v_mfma_f32_16x16x32_f16 v[62:65], v[160:163], v[184:187], v[62:65]
	v_mfma_f32_16x16x32_f16 v[50:53], v[148:151], v[192:195], v[50:53]
	v_mfma_f32_16x16x32_f16 v[46:49], v[160:163], v[192:195], v[46:49]
	v_mfma_f32_16x16x32_f16 v[34:37], v[148:151], v[200:203], v[34:37]
	v_mfma_f32_16x16x32_f16 v[30:33], v[160:163], v[200:203], v[30:33]
	v_mfma_f32_16x16x32_f16 v[18:21], v[148:151], v[218:221], v[18:21]
	v_mfma_f32_16x16x32_f16 v[10:13], v[160:163], v[218:221], v[10:13]
	v_mfma_f32_16x16x32_f16 v[58:61], v[164:167], v[180:183], v[58:61]
	v_mfma_f32_16x16x32_f16 v[54:57], v[172:175], v[180:183], v[54:57]
	v_mfma_f32_16x16x32_f16 v[42:45], v[164:167], v[188:191], v[42:45]
	v_mfma_f32_16x16x32_f16 v[38:41], v[172:175], v[188:191], v[38:41]
	v_mfma_f32_16x16x32_f16 v[26:29], v[164:167], v[196:199], v[26:29]
	v_mfma_f32_16x16x32_f16 v[22:25], v[172:175], v[196:199], v[22:25]
	v_mfma_f32_16x16x32_f16 v[6:9], v[164:167], v[204:207], v[6:9]
	v_mfma_f32_16x16x32_f16 v[2:5], v[172:175], v[204:207], v[2:5]
	v_mfma_f32_16x16x32_f16 v[58:61], v[168:171], v[184:187], v[58:61]
	v_mfma_f32_16x16x32_f16 v[54:57], v[176:179], v[184:187], v[54:57]
	v_mfma_f32_16x16x32_f16 v[42:45], v[168:171], v[192:195], v[42:45]
	v_mfma_f32_16x16x32_f16 v[38:41], v[176:179], v[192:195], v[38:41]
	v_mfma_f32_16x16x32_f16 v[26:29], v[168:171], v[200:203], v[26:29]
	v_mfma_f32_16x16x32_f16 v[22:25], v[176:179], v[200:203], v[22:25]
	v_mfma_f32_16x16x32_f16 v[6:9], v[168:171], v[218:221], v[6:9]
	v_mfma_f32_16x16x32_f16 v[2:5], v[176:179], v[218:221], v[2:5]
	s_barrier
	s_add_i32 s82, s82, 2
	s_add_u32 s50, s50, 0x100
	s_addc_u32 s51, s51, 0
	s_add_u32 s76, s76, 0x100
	s_addc_u32 s77, s77, 0
	s_cmp_gt_u32 s82, 13
	s_cbranch_scc0 .LBB0_269
	s_and_b64 vcc, exec, s[14:15]
	s_cbranch_vccz .LBB0_272
	s_barrier

; #define PG8_STAGE(bufoff, gbase, voff) do { _Pragma("unroll") for (int _i = 0; _i < 2; ++_i) \
;         __builtin_amdgcn_global_load_lds((const unsigned*)((const char*)(gbase) + (voff)[_i]), (PG8_LAS unsigned*)(lds + (bufoff) + ldsw + _i * 8192), 16, 0, 0); } while (0)
; #define PG8_LDA(dst, b, h) do { _Pragma("unroll") for (int m = 0; m < 4; ++m) _Pragma("unroll") for (int k = 0; k < 2; ++k) dst[m][k] = *(const PG8_LAS bf16x8*)(lds + PG8_SA(b, h) + aoff + m * 2048 + k * 1024); } while (0)
; #define PG8_LDB(dst, b, h) do { _Pragma("unroll") for (int n = 0; n < 2; ++n) _Pragma("unroll") for (int k = 0; k < 2; ++k) dst[n][k] = *(const PG8_LAS bf16x8*)(lds + PG8_SB(b, h) + boff + n * 2048 + k * 1024); } while (0)
; #define PG8_MMA(ai, bj, At, Bt) do { __builtin_amdgcn_s_setprio(1); _Pragma("unroll") for (int m = 0; m < 4; ++m) _Pragma("unroll") for (int n = 0; n < 2; ++n) _Pragma("unroll") for (int k = 0; k < 2; ++k) \
;         acc[ai][bj][m][n] = __builtin_amdgcn_mfma_f32_16x16x32_f16(Bt[n][k], At[m][k], acc[ai][bj][m][n], 0, 0, 0); __builtin_amdgcn_s_setprio(0); } while (0)
; #define PG8_WAIT_V(n) asm volatile("s_waitcnt vmcnt(" #n ")" ::: "memory")
; #define PG8_WAIT_L(n) asm volatile("s_waitcnt lgkmcnt(" #n ")" ::: "memory")
; #define PG8_BAR __builtin_amdgcn_s_barrier()
; #define PG8_SCHED __builtin_amdgcn_sched_barrier(0)
; template <class Epi, class Sched, bool ALIGN_EPI = false, bool SP2 = false>
; __device__ __forceinline__ void gemm_phase(PG8_LAS unsigned char* lds, const Gemm g, const Sched& S, const Epi& E) {
;     ...
;         for (int t = 0; t < nt; t += 2) {
;             const bool last = (t == nt - 2);
;             const char* a1 = cA + (size_t)(t + 1) * kstep;
;             const char* a2 = last ? nA : cA + (size_t)(t + 2) * kstep; const char* b2 = last ? nB : cB + (size_t)(t + 2) * kstep;
;             const char* a3 = a2 + kstep; const char* b3 = b2 + kstep;
;             if (last && has_next) S.a_ready(nxt);
;             if constexpr (SP2) {
;             PG8_LDB(B0, 0, 0); PG8_LDB(B1, 0, 1); PG8_SCHED; PG8_LDA(At, 0, 0); PG8_STAGE(PG8_SA(1, 1), a1 + hstep, voffA);
;             PG8_WAIT_V(8); PG8_WAIT_L(0); PG8_BAR; PG8_MMA(0, 0, At, B0); PG8_MMA(0, 1, At, B1); PG8_BAR; PG8_SCHED;
;             PG8_LDA(At, 0, 1); PG8_STAGE(PG8_SB(0, 0), b2, voffB); PG8_STAGE(PG8_SB(0, 1), b2 + hstep, voffB); PG8_STAGE(PG8_SA(0, 0), a2, voffA);
.LBB0_784:
	s_add_u32 s13, s16, 0xfffc0080
	s_addc_u32 s22, s17, -1
	s_add_i32 s92, 0, 0x10000
	s_cmp_eq_u32 s12, 12
	s_cselect_b32 s25, s29, s22
	s_cselect_b32 s24, s43, s13
	v_add_u32_e32 v1, s92, v223
	s_cselect_b32 s23, s41, vcc_hi
	s_cselect_b32 s22, s58, vcc_lo
	s_add_i32 s13, 0, 0x14000
	ds_read_b128 v[66:69], v1
	ds_read_b128 v[74:77], v1 offset:1024
	ds_read_b128 v[78:81], v1 offset:2048
	ds_read_b128 v[82:85], v1 offset:3072
	v_add_u32_e32 v1, s13, v223
	ds_read_b128 v[86:89], v1
	ds_read_b128 v[90:93], v1 offset:1024
	ds_read_b128 v[94:97], v1 offset:2048
	ds_read_b128 v[98:101], v1 offset:3072
	v_lshl_add_u64 v[208:209], s[16:17], 0, v[196:197]
	s_add_i32 m0, s28, 0xc000
	ds_read_b128 v[158:161], v226
	ds_read_b128 v[170:173], v226 offset:1024
	ds_read_b128 v[174:177], v226 offset:2048
	ds_read_b128 v[178:181], v226 offset:3072
	ds_read_b128 v[182:185], v226 offset:4096
	ds_read_b128 v[186:189], v226 offset:5120
	ds_read_b128 v[200:203], v226 offset:6144
	ds_read_b128 v[204:207], v226 offset:7168
	global_load_lds_dwordx4 v[208:209], off
	v_lshl_add_u64 v[208:209], s[16:17], 0, v[198:199]
	s_add_i32 m0, s28, 0xe000
	s_nop 0
	global_load_lds_dwordx4 v[208:209], off
	s_waitcnt vmcnt(8)
	s_waitcnt lgkmcnt(0)
	s_barrier
	v_mfma_f32_16x16x32_f16 v[166:169], v[66:69], v[158:161], v[166:169]
	v_mfma_f32_16x16x32_f16 v[162:165], v[78:81], v[158:161], v[162:165]
	v_mfma_f32_16x16x32_f16 v[146:149], v[66:69], v[174:177], v[146:149]
	v_mfma_f32_16x16x32_f16 v[142:145], v[78:81], v[174:177], v[142:145]
	v_mfma_f32_16x16x32_f16 v[130:133], v[66:69], v[182:185], v[130:133]
	v_mfma_f32_16x16x32_f16 v[126:129], v[78:81], v[182:185], v[126:129]
	v_mfma_f32_16x16x32_f16 v[114:117], v[66:69], v[200:203], v[114:117]
	v_mfma_f32_16x16x32_f16 v[110:113], v[78:81], v[200:203], v[110:113]
	v_mfma_f32_16x16x32_f16 v[166:169], v[74:77], v[170:173], v[166:169]
	v_mfma_f32_16x16x32_f16 v[162:165], v[82:85], v[170:173], v[162:165]
	v_mfma_f32_16x16x32_f16 v[146:149], v[74:77], v[178:181], v[146:149]
	v_mfma_f32_16x16x32_f16 v[142:145], v[82:85], v[178:181], v[142:145]
	v_mfma_f32_16x16x32_f16 v[130:133], v[74:77], v[186:189], v[130:133]
	v_mfma_f32_16x16x32_f16 v[126:129], v[82:85], v[186:189], v[126:129]
	v_mfma_f32_16x16x32_f16 v[114:117], v[74:77], v[204:207], v[114:117]
	v_mfma_f32_16x16x32_f16 v[110:113], v[82:85], v[204:207], v[110:113]
	v_mfma_f32_16x16x32_f16 v[154:157], v[86:89], v[158:161], v[154:157]
	v_mfma_f32_16x16x32_f16 v[150:153], v[94:97], v[158:161], v[150:153]
	v_mfma_f32_16x16x32_f16 v[138:141], v[86:89], v[174:177], v[138:141]
	v_mfma_f32_16x16x32_f16 v[134:137], v[94:97], v[174:177], v[134:137]
	v_mfma_f32_16x16x32_f16 v[122:125], v[86:89], v[182:185], v[122:125]
	v_mfma_f32_16x16x32_f16 v[118:121], v[94:97], v[182:185], v[118:121]
	v_mfma_f32_16x16x32_f16 v[106:109], v[86:89], v[200:203], v[106:109]
	v_mfma_f32_16x16x32_f16 v[102:105], v[94:97], v[200:203], v[102:105]
	v_mfma_f32_16x16x32_f16 v[154:157], v[90:93], v[170:173], v[154:157]
	v_mfma_f32_16x16x32_f16 v[150:153], v[98:101], v[170:173], v[150:153]
	v_mfma_f32_16x16x32_f16 v[138:141], v[90:93], v[178:181], v[138:141]
	v_mfma_f32_16x16x32_f16 v[134:137], v[98:101], v[178:181], v[134:137]
	v_mfma_f32_16x16x32_f16 v[122:125], v[90:93], v[186:189], v[122:125]
	v_mfma_f32_16x16x32_f16 v[118:121], v[98:101], v[186:189], v[118:121]
	v_mfma_f32_16x16x32_f16 v[106:109], v[90:93], v[204:207], v[106:109]
	v_mfma_f32_16x16x32_f16 v[102:105], v[98:101], v[204:207], v[102:105]
	s_barrier
	s_add_i32 s92, s92, s11
	v_lshl_add_u64 v[208:209], s[22:23], 0, v[192:193]
	s_mov_b32 m0, s92
	ds_read_b128 v[158:161], v226 offset:16384
	ds_read_b128 v[170:173], v226 offset:17408
	ds_read_b128 v[174:177], v226 offset:18432
	ds_read_b128 v[178:181], v226 offset:19456
	ds_read_b128 v[182:185], v226 offset:20480
	ds_read_b128 v[186:189], v226 offset:21504
	ds_read_b128 v[200:203], v226 offset:22528
	ds_read_b128 v[204:207], v226 offset:23552
	global_load_lds_dwordx4 v[208:209], off
	s_add_i32 m0, s92, 0x2000
	s_add_u32 s92, s22, 0x40000
	v_lshl_add_u64 v[210:211], s[22:23], 0, v[14:15]
	s_addc_u32 s93, s23, 0
	s_add_i32 s13, s13, s11
	global_load_lds_dwordx4 v[210:211], off
	v_lshl_add_u64 v[212:213], s[92:93], 0, v[192:193]
	s_mov_b32 m0, s13
	v_lshl_add_u64 v[214:215], s[24:25], 0, v[190:191]
	global_load_lds_dwordx4 v[212:213], off
	v_lshl_add_u64 v[212:213], s[92:93], 0, v[14:15]
	s_add_i32 m0, s13, 0x2000
	s_nop 0
	global_load_lds_dwordx4 v[212:213], off
	v_lshl_add_u64 v[212:213], s[24:25], 0, v[194:195]
	s_mov_b32 m0, s28
	s_nop 0
	global_load_lds_dwordx4 v[212:213], off
	s_mov_b32 m0, s33
	s_nop 0
	global_load_lds_dwordx4 v[214:215], off
	s_waitcnt vmcnt(8)
	s_waitcnt lgkmcnt(0)
	s_barrier
; #define PG8_STAGE(bufoff, gbase, voff) do { _Pragma("unroll") for (int _i = 0; _i < 2; ++_i) \
;         __builtin_amdgcn_global_load_lds((const unsigned*)((const char*)(gbase) + (voff)[_i]), (PG8_LAS unsigned*)(lds + (bufoff) + ldsw + _i * 8192), 16, 0, 0); } while (0)
; #define PG8_LDA(dst, b, h) do { _Pragma("unroll") for (int m = 0; m < 4; ++m) _Pragma("unroll") for (int k = 0; k < 2; ++k) dst[m][k] = *(const PG8_LAS bf16x8*)(lds + PG8_SA(b, h) + aoff + m * 2048 + k * 1024); } while (0)
; #define PG8_LDB(dst, b, h) do { _Pragma("unroll") for (int n = 0; n < 2; ++n) _Pragma("unroll") for (int k = 0; k < 2; ++k) dst[n][k] = *(const PG8_LAS bf16x8*)(lds + PG8_SB(b, h) + boff + n * 2048 + k * 1024); } while (0)
; #define PG8_MMA(ai, bj, At, Bt) do { __builtin_amdgcn_s_setprio(1); _Pragma("unroll") for (int m = 0; m < 4; ++m) _Pragma("unroll") for (int n = 0; n < 2; ++n) _Pragma("unroll") for (int k = 0; k < 2; ++k) \
;         acc[ai][bj][m][n] = __builtin_amdgcn_mfma_f32_16x16x32_f16(Bt[n][k], At[m][k], acc[ai][bj][m][n], 0, 0, 0); __builtin_amdgcn_s_setprio(0); } while (0)
; #define PG8_WAIT_V(n) asm volatile("s_waitcnt vmcnt(" #n ")" ::: "memory")
; #define PG8_WAIT_L(n) asm volatile("s_waitcnt lgkmcnt(" #n ")" ::: "memory")
; #define PG8_BAR __builtin_amdgcn_s_barrier()
; #define PG8_SCHED __builtin_amdgcn_sched_barrier(0)
; template <class Epi, class Sched, bool ALIGN_EPI = false, bool SP2 = false>
; __device__ __forceinline__ void gemm_phase(PG8_LAS unsigned char* lds, const Gemm g, const Sched& S, const Epi& E) {
;     ...
;             PG8_LDA(At, 0, 1); PG8_STAGE(PG8_SB(0, 0), b2, voffB); PG8_STAGE(PG8_SB(0, 1), b2 + hstep, voffB); PG8_STAGE(PG8_SA(0, 0), a2, voffA);
;             PG8_WAIT_V(8); PG8_WAIT_L(0); PG8_BAR; PG8_MMA(1, 0, At, B0); PG8_MMA(1, 1, At, B1); PG8_BAR; PG8_SCHED;
;             PG8_LDB(B0, 1, 0); PG8_LDB(B1, 1, 1); PG8_SCHED; PG8_LDA(At, 1, 0); PG8_STAGE(PG8_SA(0, 1), a2 + hstep, voffA);
;             PG8_WAIT_V(8); PG8_WAIT_L(0); PG8_BAR; PG8_MMA(0, 0, At, B0); PG8_MMA(0, 1, At, B1); PG8_BAR; PG8_SCHED;
	v_mfma_f32_16x16x32_f16 v[70:73], v[66:69], v[158:161], v[70:73]
	v_mfma_f32_16x16x32_f16 v[62:65], v[78:81], v[158:161], v[62:65]
	v_mfma_f32_16x16x32_f16 v[50:53], v[66:69], v[174:177], v[50:53]
	v_mfma_f32_16x16x32_f16 v[46:49], v[78:81], v[174:177], v[46:49]
	v_mfma_f32_16x16x32_f16 v[34:37], v[66:69], v[182:185], v[34:37]
	v_mfma_f32_16x16x32_f16 v[30:33], v[78:81], v[182:185], v[30:33]
	v_mfma_f32_16x16x32_f16 v[18:21], v[66:69], v[200:203], v[18:21]
	v_mfma_f32_16x16x32_f16 v[10:13], v[78:81], v[200:203], v[10:13]
	v_mfma_f32_16x16x32_f16 v[70:73], v[74:77], v[170:173], v[70:73]
	v_mfma_f32_16x16x32_f16 v[62:65], v[82:85], v[170:173], v[62:65]
	v_mfma_f32_16x16x32_f16 v[50:53], v[74:77], v[178:181], v[50:53]
	v_mfma_f32_16x16x32_f16 v[46:49], v[82:85], v[178:181], v[46:49]
	v_mfma_f32_16x16x32_f16 v[34:37], v[74:77], v[186:189], v[34:37]
	v_mfma_f32_16x16x32_f16 v[30:33], v[82:85], v[186:189], v[30:33]
	v_mfma_f32_16x16x32_f16 v[18:21], v[74:77], v[204:207], v[18:21]
	v_mfma_f32_16x16x32_f16 v[10:13], v[82:85], v[204:207], v[10:13]
	v_mfma_f32_16x16x32_f16 v[58:61], v[86:89], v[158:161], v[58:61]
	v_mfma_f32_16x16x32_f16 v[54:57], v[94:97], v[158:161], v[54:57]
	v_mfma_f32_16x16x32_f16 v[42:45], v[86:89], v[174:177], v[42:45]
	v_mfma_f32_16x16x32_f16 v[38:41], v[94:97], v[174:177], v[38:41]
	v_mfma_f32_16x16x32_f16 v[26:29], v[86:89], v[182:185], v[26:29]
	v_mfma_f32_16x16x32_f16 v[22:25], v[94:97], v[182:185], v[22:25]
	v_mfma_f32_16x16x32_f16 v[6:9], v[86:89], v[200:203], v[6:9]
	v_mfma_f32_16x16x32_f16 v[2:5], v[94:97], v[200:203], v[2:5]
	v_mfma_f32_16x16x32_f16 v[58:61], v[90:93], v[170:173], v[58:61]
	v_mfma_f32_16x16x32_f16 v[54:57], v[98:101], v[170:173], v[54:57]
	v_mfma_f32_16x16x32_f16 v[42:45], v[90:93], v[178:181], v[42:45]
	v_mfma_f32_16x16x32_f16 v[38:41], v[98:101], v[178:181], v[38:41]
	v_mfma_f32_16x16x32_f16 v[26:29], v[90:93], v[186:189], v[26:29]
	v_mfma_f32_16x16x32_f16 v[22:25], v[98:101], v[186:189], v[22:25]
	v_mfma_f32_16x16x32_f16 v[6:9], v[90:93], v[204:207], v[6:9]
	v_mfma_f32_16x16x32_f16 v[2:5], v[98:101], v[204:207], v[2:5]
	s_barrier
	s_add_i32 s13, 0, 0x18000
	v_add_u32_e32 v1, s13, v223
	s_add_i32 s92, 0, 0x1c000
	ds_read_b128 v[66:69], v1
	ds_read_b128 v[74:77], v1 offset:1024
	ds_read_b128 v[78:81], v1 offset:2048
	ds_read_b128 v[82:85], v1 offset:3072
	v_add_u32_e32 v1, s92, v223
	ds_read_b128 v[86:89], v1
	ds_read_b128 v[90:93], v1 offset:1024
	ds_read_b128 v[94:97], v1 offset:2048
	ds_read_b128 v[98:101], v1 offset:3072
	s_add_u32 s24, s24, 0x40000
	s_addc_u32 s25, s25, 0
	s_mov_b32 m0, s49
	v_lshl_add_u64 v[218:219], s[24:25], 0, v[194:195]
	ds_read_b128 v[158:161], v226 offset:32768
	ds_read_b128 v[170:173], v226 offset:33792
	ds_read_b128 v[174:177], v226 offset:34816
	ds_read_b128 v[178:181], v226 offset:35840
	ds_read_b128 v[182:185], v226 offset:36864
	ds_read_b128 v[186:189], v226 offset:37888
	ds_read_b128 v[200:203], v226 offset:38912
	ds_read_b128 v[204:207], v226 offset:39936
	global_load_lds_dwordx4 v[218:219], off
	v_lshl_add_u64 v[218:219], s[24:25], 0, v[190:191]
	s_mov_b32 m0, s71
	s_nop 0
	global_load_lds_dwordx4 v[218:219], off
	s_waitcnt vmcnt(8)
	s_waitcnt lgkmcnt(0)
	s_barrier
	v_mfma_f32_16x16x32_f16 v[166:169], v[66:69], v[158:161], v[166:169]
	v_mfma_f32_16x16x32_f16 v[162:165], v[78:81], v[158:161], v[162:165]
	v_mfma_f32_16x16x32_f16 v[146:149], v[66:69], v[174:177], v[146:149]
	v_mfma_f32_16x16x32_f16 v[142:145], v[78:81], v[174:177], v[142:145]
	v_mfma_f32_16x16x32_f16 v[130:133], v[66:69], v[182:185], v[130:133]
	v_mfma_f32_16x16x32_f16 v[126:129], v[78:81], v[182:185], v[126:129]
	v_mfma_f32_16x16x32_f16 v[114:117], v[66:69], v[200:203], v[114:117]
	v_mfma_f32_16x16x32_f16 v[110:113], v[78:81], v[200:203], v[110:113]
	v_mfma_f32_16x16x32_f16 v[166:169], v[74:77], v[170:173], v[166:169]
	v_mfma_f32_16x16x32_f16 v[162:165], v[82:85], v[170:173], v[162:165]
	v_mfma_f32_16x16x32_f16 v[146:149], v[74:77], v[178:181], v[146:149]
	v_mfma_f32_16x16x32_f16 v[142:145], v[82:85], v[178:181], v[142:145]
	v_mfma_f32_16x16x32_f16 v[130:133], v[74:77], v[186:189], v[130:133]
	v_mfma_f32_16x16x32_f16 v[126:129], v[82:85], v[186:189], v[126:129]
	v_mfma_f32_16x16x32_f16 v[114:117], v[74:77], v[204:207], v[114:117]
	v_mfma_f32_16x16x32_f16 v[110:113], v[82:85], v[204:207], v[110:113]
	v_mfma_f32_16x16x32_f16 v[154:157], v[86:89], v[158:161], v[154:157]
	v_mfma_f32_16x16x32_f16 v[150:153], v[94:97], v[158:161], v[150:153]
	v_mfma_f32_16x16x32_f16 v[138:141], v[86:89], v[174:177], v[138:141]
	v_mfma_f32_16x16x32_f16 v[134:137], v[94:97], v[174:177], v[134:137]
	v_mfma_f32_16x16x32_f16 v[122:125], v[86:89], v[182:185], v[122:125]
	v_mfma_f32_16x16x32_f16 v[118:121], v[94:97], v[182:185], v[118:121]
	v_mfma_f32_16x16x32_f16 v[106:109], v[86:89], v[200:203], v[106:109]
	v_mfma_f32_16x16x32_f16 v[102:105], v[94:97], v[200:203], v[102:105]
	v_mfma_f32_16x16x32_f16 v[154:157], v[90:93], v[170:173], v[154:157]
	v_mfma_f32_16x16x32_f16 v[150:153], v[98:101], v[170:173], v[150:153]
	v_mfma_f32_16x16x32_f16 v[138:141], v[90:93], v[178:181], v[138:141]
	v_mfma_f32_16x16x32_f16 v[134:137], v[98:101], v[178:181], v[134:137]
	v_mfma_f32_16x16x32_f16 v[122:125], v[90:93], v[186:189], v[122:125]
	v_mfma_f32_16x16x32_f16 v[118:121], v[98:101], v[186:189], v[118:121]
	v_mfma_f32_16x16x32_f16 v[106:109], v[90:93], v[204:207], v[106:109]
	v_mfma_f32_16x16x32_f16 v[102:105], v[98:101], v[204:207], v[102:105]
	s_barrier
; #define PG8_STAGE(bufoff, gbase, voff) do { _Pragma("unroll") for (int _i = 0; _i < 2; ++_i) \
;         __builtin_amdgcn_global_load_lds((const unsigned*)((const char*)(gbase) + (voff)[_i]), (PG8_LAS unsigned*)(lds + (bufoff) + ldsw + _i * 8192), 16, 0, 0); } while (0)
; #define PG8_LDA(dst, b, h) do { _Pragma("unroll") for (int m = 0; m < 4; ++m) _Pragma("unroll") for (int k = 0; k < 2; ++k) dst[m][k] = *(const PG8_LAS bf16x8*)(lds + PG8_SA(b, h) + aoff + m * 2048 + k * 1024); } while (0)
; #define PG8_WAIT_V(n) asm volatile("s_waitcnt vmcnt(" #n ")" ::: "memory")
; template <class Epi, class Sched, bool ALIGN_EPI = false, bool SP2 = false>
; __device__ __forceinline__ void gemm_phase(PG8_LAS unsigned char* lds, const Gemm g, const Sched& S, const Epi& E) {
;     ...
;             PG8_LDA(At, 1, 1); PG8_STAGE(PG8_SB(1, 0), b3, voffB); PG8_STAGE(PG8_SB(1, 1), b3 + hstep, voffB); PG8_STAGE(PG8_SA(1, 0), a3, voffA);
;             PG8_WAIT_V(8); PG8_WAIT_L(0); PG8_BAR; PG8_MMA(1, 0, At, B0); PG8_MMA(1, 1, At, B1); PG8_BAR; PG8_SCHED;
;             } else {
;             PG8_LDB(B0, 0, 0); PG8_SCHED; PG8_LDA(At, 0, 0); PG8_STAGE(PG8_SA(1, 1), a1 + hstep, voffA);
;             PG8_WAIT_L(8); PG8_BAR; PG8_WAIT_L(0); PG8_MMA(0, 0, At, B0); PG8_BAR; PG8_SCHED;
;             PG8_LDB(B1, 0, 1); PG8_STAGE(PG8_SB(0, 0), b2, voffB);
;             PG8_BAR; PG8_WAIT_L(0); PG8_MMA(0, 1, At, B1); PG8_BAR;
;             PG8_LDA(At, 0, 1); PG8_STAGE(PG8_SA(0, 0), a2, voffA);
;             PG8_BAR; PG8_WAIT_L(0); PG8_MMA(1, 0, At, B0); PG8_BAR; PG8_SCHED;
;             PG8_STAGE(PG8_SB(0, 1), b2 + hstep, voffB);
;             PG8_WAIT_V(6); PG8_BAR; PG8_MMA(1, 1, At, B1); PG8_BAR;
;             PG8_LDB(B0, 1, 0); PG8_SCHED; PG8_LDA(At, 1, 0); PG8_STAGE(PG8_SA(0, 1), a2 + hstep, voffA);
;             PG8_WAIT_L(8); PG8_BAR; PG8_WAIT_L(0); PG8_MMA(0, 0, At, B0); PG8_BAR; PG8_SCHED;
;             PG8_LDB(B1, 1, 1); PG8_STAGE(PG8_SB(1, 0), b3, voffB);
;             PG8_BAR; PG8_WAIT_L(0); PG8_MMA(0, 1, At, B1); PG8_BAR;
;             PG8_LDA(At, 1, 1); PG8_STAGE(PG8_SA(1, 0), a3, voffA);
;             PG8_BAR; PG8_WAIT_L(0); PG8_MMA(1, 0, At, B0); PG8_BAR; PG8_SCHED;
;             PG8_STAGE(PG8_SB(1, 1), b3 + hstep, voffB);
;             PG8_WAIT_V(6); PG8_BAR; PG8_MMA(1, 1, At, B1); PG8_BAR;
;             }
;         }
;         if constexpr (ALIGN_EPI) { if (wr == 0) PG8_BAR; }
	s_add_i32 s13, s13, s11
	v_lshl_add_u64 v[208:209], v[208:209], 0, s[34:35]
	s_mov_b32 m0, s13
	ds_read_b128 v[158:161], v226 offset:49152
	ds_read_b128 v[170:173], v226 offset:50176
	ds_read_b128 v[174:177], v226 offset:51200
	ds_read_b128 v[178:181], v226 offset:52224
	ds_read_b128 v[182:185], v226 offset:53248
	ds_read_b128 v[186:189], v226 offset:54272
	ds_read_b128 v[200:203], v226 offset:55296
	ds_read_b128 v[204:207], v226 offset:56320
	global_load_lds_dwordx4 v[208:209], off
	s_add_i32 m0, s13, 0x2000
	s_add_u32 s22, s22, 0x40080
	v_lshl_add_u64 v[208:209], v[210:211], 0, s[34:35]
	s_addc_u32 s23, s23, 0
	s_add_i32 s13, s92, s11
	global_load_lds_dwordx4 v[208:209], off
	v_lshl_add_u64 v[208:209], s[22:23], 0, v[192:193]
	s_mov_b32 m0, s13
	s_nop 0
	global_load_lds_dwordx4 v[208:209], off
	v_lshl_add_u64 v[208:209], s[22:23], 0, v[14:15]
	s_add_i32 m0, s13, 0x2000
	s_nop 0
	global_load_lds_dwordx4 v[208:209], off
	v_lshl_add_u64 v[208:209], v[212:213], 0, s[34:35]
	s_mov_b32 m0, s73
	s_nop 0
	global_load_lds_dwordx4 v[208:209], off
	v_lshl_add_u64 v[208:209], v[214:215], 0, s[34:35]
	s_mov_b32 m0, s76
	s_nop 0
	global_load_lds_dwordx4 v[208:209], off
	s_waitcnt vmcnt(8)
	s_waitcnt lgkmcnt(0)
	s_barrier
	v_mfma_f32_16x16x32_f16 v[70:73], v[66:69], v[158:161], v[70:73]
	v_mfma_f32_16x16x32_f16 v[62:65], v[78:81], v[158:161], v[62:65]
	v_mfma_f32_16x16x32_f16 v[50:53], v[66:69], v[174:177], v[50:53]
	v_mfma_f32_16x16x32_f16 v[46:49], v[78:81], v[174:177], v[46:49]
	v_mfma_f32_16x16x32_f16 v[34:37], v[66:69], v[182:185], v[34:37]
	v_mfma_f32_16x16x32_f16 v[30:33], v[78:81], v[182:185], v[30:33]
	v_mfma_f32_16x16x32_f16 v[18:21], v[66:69], v[200:203], v[18:21]
	v_mfma_f32_16x16x32_f16 v[10:13], v[78:81], v[200:203], v[10:13]
	v_mfma_f32_16x16x32_f16 v[70:73], v[74:77], v[170:173], v[70:73]
	v_mfma_f32_16x16x32_f16 v[62:65], v[82:85], v[170:173], v[62:65]
	v_mfma_f32_16x16x32_f16 v[50:53], v[74:77], v[178:181], v[50:53]
	v_mfma_f32_16x16x32_f16 v[46:49], v[82:85], v[178:181], v[46:49]
	v_mfma_f32_16x16x32_f16 v[34:37], v[74:77], v[186:189], v[34:37]
	v_mfma_f32_16x16x32_f16 v[30:33], v[82:85], v[186:189], v[30:33]
	v_mfma_f32_16x16x32_f16 v[18:21], v[74:77], v[204:207], v[18:21]
	v_mfma_f32_16x16x32_f16 v[10:13], v[82:85], v[204:207], v[10:13]
	v_mfma_f32_16x16x32_f16 v[58:61], v[86:89], v[158:161], v[58:61]
	v_mfma_f32_16x16x32_f16 v[54:57], v[94:97], v[158:161], v[54:57]
	v_mfma_f32_16x16x32_f16 v[42:45], v[86:89], v[174:177], v[42:45]
	v_mfma_f32_16x16x32_f16 v[38:41], v[94:97], v[174:177], v[38:41]
	v_mfma_f32_16x16x32_f16 v[26:29], v[86:89], v[182:185], v[26:29]
	v_mfma_f32_16x16x32_f16 v[22:25], v[94:97], v[182:185], v[22:25]
	v_mfma_f32_16x16x32_f16 v[6:9], v[86:89], v[200:203], v[6:9]
	v_mfma_f32_16x16x32_f16 v[2:5], v[94:97], v[200:203], v[2:5]
	v_mfma_f32_16x16x32_f16 v[58:61], v[90:93], v[170:173], v[58:61]
	v_mfma_f32_16x16x32_f16 v[54:57], v[98:101], v[170:173], v[54:57]
	v_mfma_f32_16x16x32_f16 v[42:45], v[90:93], v[178:181], v[42:45]
	v_mfma_f32_16x16x32_f16 v[38:41], v[98:101], v[178:181], v[38:41]
	v_mfma_f32_16x16x32_f16 v[26:29], v[90:93], v[186:189], v[26:29]
	v_mfma_f32_16x16x32_f16 v[22:25], v[98:101], v[186:189], v[22:25]
	v_mfma_f32_16x16x32_f16 v[6:9], v[90:93], v[204:207], v[6:9]
	v_mfma_f32_16x16x32_f16 v[2:5], v[98:101], v[204:207], v[2:5]
	s_barrier
	s_add_i32 s12, s12, 2
	s_add_u32 s16, s16, 0x100
	s_addc_u32 s17, s17, 0
	s_add_u32 vcc_lo, vcc_lo, 0x100
	s_addc_u32 vcc_hi, vcc_hi, 0
	s_cmp_gt_u32 s12, 13
	s_cbranch_scc0 .LBB0_784
	s_and_b64 vcc, exec, s[14:15]
	s_cbranch_vccz .LBB0_787
	s_barrier

; #define PG8_STAGE(bufoff, gbase, voff) do { _Pragma("unroll") for (int _i = 0; _i < 2; ++_i) \
;         __builtin_amdgcn_global_load_lds((const unsigned*)((const char*)(gbase) + (voff)[_i]), (PG8_LAS unsigned*)(lds + (bufoff) + ldsw + _i * 8192), 16, 0, 0); } while (0)
; #define PG8_LDA(dst, b, h) do { _Pragma("unroll") for (int m = 0; m < 4; ++m) _Pragma("unroll") for (int k = 0; k < 2; ++k) dst[m][k] = *(const PG8_LAS bf16x8*)(lds + PG8_SA(b, h) + aoff + m * 2048 + k * 1024); } while (0)
; #define PG8_LDB(dst, b, h) do { _Pragma("unroll") for (int n = 0; n < 2; ++n) _Pragma("unroll") for (int k = 0; k < 2; ++k) dst[n][k] = *(const PG8_LAS bf16x8*)(lds + PG8_SB(b, h) + boff + n * 2048 + k * 1024); } while (0)
; #define PG8_MMA(ai, bj, At, Bt) do { __builtin_amdgcn_s_setprio(1); _Pragma("unroll") for (int m = 0; m < 4; ++m) _Pragma("unroll") for (int n = 0; n < 2; ++n) _Pragma("unroll") for (int k = 0; k < 2; ++k) \
;         acc[ai][bj][m][n] = __builtin_amdgcn_mfma_f32_16x16x32_f16(Bt[n][k], At[m][k], acc[ai][bj][m][n], 0, 0, 0); __builtin_amdgcn_s_setprio(0); } while (0)
; #define PG8_WAIT_V(n) asm volatile("s_waitcnt vmcnt(" #n ")" ::: "memory")
; #define PG8_WAIT_L(n) asm volatile("s_waitcnt lgkmcnt(" #n ")" ::: "memory")
; #define PG8_BAR __builtin_amdgcn_s_barrier()
; #define PG8_SCHED __builtin_amdgcn_sched_barrier(0)
; template <class Epi, class Sched, bool ALIGN_EPI = false, bool SP2 = false>
; __device__ __forceinline__ void gemm_phase(PG8_LAS unsigned char* lds, const Gemm g, const Sched& S, const Epi& E) {
;     ...
;         for (int t = 0; t < nt; t += 2) {
;             const bool last = (t == nt - 2);
;             const char* a1 = cA + (size_t)(t + 1) * kstep;
;             const char* a2 = last ? nA : cA + (size_t)(t + 2) * kstep; const char* b2 = last ? nB : cB + (size_t)(t + 2) * kstep;
;             const char* a3 = a2 + kstep; const char* b3 = b2 + kstep;
;             if (last && has_next) S.a_ready(nxt);
;             if constexpr (SP2) {
;             PG8_LDB(B0, 0, 0); PG8_LDB(B1, 0, 1); PG8_SCHED; PG8_LDA(At, 0, 0); PG8_STAGE(PG8_SA(1, 1), a1 + hstep, voffA);
;             PG8_WAIT_V(8); PG8_WAIT_L(0); PG8_BAR; PG8_MMA(0, 0, At, B0); PG8_MMA(0, 1, At, B1); PG8_BAR; PG8_SCHED;
;             PG8_LDA(At, 0, 1); PG8_STAGE(PG8_SB(0, 0), b2, voffB); PG8_STAGE(PG8_SB(0, 1), b2 + hstep, voffB); PG8_STAGE(PG8_SA(0, 0), a2, voffA);
.LBB0_824:
	s_add_u32 s12, s82, 0xfffc0080
	s_addc_u32 s13, s83, -1
	s_add_i32 s92, 0, 0x10000
	s_cmp_eq_u32 vcc_hi, 12
	s_cselect_b32 s25, s27, s13
	s_cselect_b32 s24, s29, s12
	v_add_u32_e32 v1, s92, v180
	s_cselect_b32 s23, s17, vcc_lo
	s_cselect_b32 s22, s41, s58
	s_add_i32 s93, 0, 0x14000
	ds_read_b128 v[126:129], v1
	ds_read_b128 v[138:141], v1 offset:1024
	ds_read_b128 v[142:145], v1 offset:2048
	ds_read_b128 v[146:149], v1 offset:3072
	v_add_u32_e32 v1, s93, v180
	ds_read_b128 v[150:153], v1
	ds_read_b128 v[154:157], v1 offset:1024
	ds_read_b128 v[168:171], v1 offset:2048
	ds_read_b128 v[172:175], v1 offset:3072
	v_lshl_add_u64 v[212:213], s[82:83], 0, v[164:165]
	s_add_i32 m0, s28, 0xc000
	ds_read_b128 v[176:179], v182
	ds_read_b128 v[184:187], v182 offset:1024
	ds_read_b128 v[188:191], v182 offset:2048
	ds_read_b128 v[192:195], v182 offset:3072
	ds_read_b128 v[196:199], v182 offset:4096
	ds_read_b128 v[200:203], v182 offset:5120
	ds_read_b128 v[204:207], v182 offset:6144
	ds_read_b128 v[208:211], v182 offset:7168
	global_load_lds_dwordx4 v[212:213], off
	v_lshl_add_u64 v[212:213], s[82:83], 0, v[166:167]
	s_add_i32 m0, s28, 0xe000
	s_nop 0
	global_load_lds_dwordx4 v[212:213], off
	s_waitcnt vmcnt(8)
	s_waitcnt lgkmcnt(0)
	s_barrier
	v_mfma_f32_16x16x32_f16 v[134:137], v[126:129], v[176:179], v[134:137]
	v_mfma_f32_16x16x32_f16 v[130:133], v[142:145], v[176:179], v[130:133]
	v_mfma_f32_16x16x32_f16 v[114:117], v[126:129], v[188:191], v[114:117]
	v_mfma_f32_16x16x32_f16 v[110:113], v[142:145], v[188:191], v[110:113]
	v_mfma_f32_16x16x32_f16 v[98:101], v[126:129], v[196:199], v[98:101]
	v_mfma_f32_16x16x32_f16 v[94:97], v[142:145], v[196:199], v[94:97]
	v_mfma_f32_16x16x32_f16 v[82:85], v[126:129], v[204:207], v[82:85]
	v_mfma_f32_16x16x32_f16 v[78:81], v[142:145], v[204:207], v[78:81]
	v_mfma_f32_16x16x32_f16 v[134:137], v[138:141], v[184:187], v[134:137]
	v_mfma_f32_16x16x32_f16 v[130:133], v[146:149], v[184:187], v[130:133]
	v_mfma_f32_16x16x32_f16 v[114:117], v[138:141], v[192:195], v[114:117]
	v_mfma_f32_16x16x32_f16 v[110:113], v[146:149], v[192:195], v[110:113]
	v_mfma_f32_16x16x32_f16 v[98:101], v[138:141], v[200:203], v[98:101]
	v_mfma_f32_16x16x32_f16 v[94:97], v[146:149], v[200:203], v[94:97]
	v_mfma_f32_16x16x32_f16 v[82:85], v[138:141], v[208:211], v[82:85]
	v_mfma_f32_16x16x32_f16 v[78:81], v[146:149], v[208:211], v[78:81]
	v_mfma_f32_16x16x32_f16 v[122:125], v[150:153], v[176:179], v[122:125]
	v_mfma_f32_16x16x32_f16 v[118:121], v[168:171], v[176:179], v[118:121]
	v_mfma_f32_16x16x32_f16 v[106:109], v[150:153], v[188:191], v[106:109]
	v_mfma_f32_16x16x32_f16 v[102:105], v[168:171], v[188:191], v[102:105]
	v_mfma_f32_16x16x32_f16 v[90:93], v[150:153], v[196:199], v[90:93]
	v_mfma_f32_16x16x32_f16 v[86:89], v[168:171], v[196:199], v[86:89]
	v_mfma_f32_16x16x32_f16 v[74:77], v[150:153], v[204:207], v[74:77]
	v_mfma_f32_16x16x32_f16 v[70:73], v[168:171], v[204:207], v[70:73]
	v_mfma_f32_16x16x32_f16 v[122:125], v[154:157], v[184:187], v[122:125]
	v_mfma_f32_16x16x32_f16 v[118:121], v[172:175], v[184:187], v[118:121]
	v_mfma_f32_16x16x32_f16 v[106:109], v[154:157], v[192:195], v[106:109]
	v_mfma_f32_16x16x32_f16 v[102:105], v[172:175], v[192:195], v[102:105]
	v_mfma_f32_16x16x32_f16 v[90:93], v[154:157], v[200:203], v[90:93]
	v_mfma_f32_16x16x32_f16 v[86:89], v[172:175], v[200:203], v[86:89]
	v_mfma_f32_16x16x32_f16 v[74:77], v[154:157], v[208:211], v[74:77]
	v_mfma_f32_16x16x32_f16 v[70:73], v[172:175], v[208:211], v[70:73]
	s_barrier
	s_add_i32 s12, s92, s11
	v_lshl_add_u64 v[212:213], s[22:23], 0, v[160:161]
	s_mov_b32 m0, s12
	ds_read_b128 v[176:179], v182 offset:16384
	ds_read_b128 v[184:187], v182 offset:17408
	ds_read_b128 v[188:191], v182 offset:18432
	ds_read_b128 v[192:195], v182 offset:19456
	ds_read_b128 v[196:199], v182 offset:20480
	ds_read_b128 v[200:203], v182 offset:21504
	ds_read_b128 v[204:207], v182 offset:22528
	ds_read_b128 v[208:211], v182 offset:23552
	global_load_lds_dwordx4 v[212:213], off
	s_add_i32 m0, s12, 0x2000
	s_add_u32 s12, s22, 0x40000
	v_lshl_add_u64 v[214:215], s[22:23], 0, v[14:15]
	s_addc_u32 s13, s23, 0
	s_add_i32 s92, s93, s11
	global_load_lds_dwordx4 v[214:215], off
	v_lshl_add_u64 v[218:219], s[12:13], 0, v[160:161]
	s_mov_b32 m0, s92
	v_lshl_add_u64 v[220:221], s[24:25], 0, v[158:159]
	global_load_lds_dwordx4 v[218:219], off
	v_lshl_add_u64 v[218:219], s[12:13], 0, v[14:15]
	s_add_i32 m0, s92, 0x2000
	s_nop 0
	global_load_lds_dwordx4 v[218:219], off
	v_lshl_add_u64 v[218:219], s[24:25], 0, v[162:163]
	s_mov_b32 m0, s28
	s_nop 0
	global_load_lds_dwordx4 v[218:219], off
	s_mov_b32 m0, s33
	s_nop 0
	global_load_lds_dwordx4 v[220:221], off
	s_waitcnt vmcnt(8)
	s_waitcnt lgkmcnt(0)
	s_barrier
; #define PG8_STAGE(bufoff, gbase, voff) do { _Pragma("unroll") for (int _i = 0; _i < 2; ++_i) \
;         __builtin_amdgcn_global_load_lds((const unsigned*)((const char*)(gbase) + (voff)[_i]), (PG8_LAS unsigned*)(lds + (bufoff) + ldsw + _i * 8192), 16, 0, 0); } while (0)
; #define PG8_LDA(dst, b, h) do { _Pragma("unroll") for (int m = 0; m < 4; ++m) _Pragma("unroll") for (int k = 0; k < 2; ++k) dst[m][k] = *(const PG8_LAS bf16x8*)(lds + PG8_SA(b, h) + aoff + m * 2048 + k * 1024); } while (0)
; #define PG8_LDB(dst, b, h) do { _Pragma("unroll") for (int n = 0; n < 2; ++n) _Pragma("unroll") for (int k = 0; k < 2; ++k) dst[n][k] = *(const PG8_LAS bf16x8*)(lds + PG8_SB(b, h) + boff + n * 2048 + k * 1024); } while (0)
; #define PG8_MMA(ai, bj, At, Bt) do { __builtin_amdgcn_s_setprio(1); _Pragma("unroll") for (int m = 0; m < 4; ++m) _Pragma("unroll") for (int n = 0; n < 2; ++n) _Pragma("unroll") for (int k = 0; k < 2; ++k) \
;         acc[ai][bj][m][n] = __builtin_amdgcn_mfma_f32_16x16x32_f16(Bt[n][k], At[m][k], acc[ai][bj][m][n], 0, 0, 0); __builtin_amdgcn_s_setprio(0); } while (0)
; #define PG8_WAIT_V(n) asm volatile("s_waitcnt vmcnt(" #n ")" ::: "memory")
; #define PG8_WAIT_L(n) asm volatile("s_waitcnt lgkmcnt(" #n ")" ::: "memory")
; #define PG8_BAR __builtin_amdgcn_s_barrier()
; #define PG8_SCHED __builtin_amdgcn_sched_barrier(0)
; template <class Epi, class Sched, bool ALIGN_EPI = false, bool SP2 = false>
; __device__ __forceinline__ void gemm_phase(PG8_LAS unsigned char* lds, const Gemm g, const Sched& S, const Epi& E) {
;     ...
;             PG8_LDA(At, 0, 1); PG8_STAGE(PG8_SB(0, 0), b2, voffB); PG8_STAGE(PG8_SB(0, 1), b2 + hstep, voffB); PG8_STAGE(PG8_SA(0, 0), a2, voffA);
;             PG8_WAIT_V(8); PG8_WAIT_L(0); PG8_BAR; PG8_MMA(1, 0, At, B0); PG8_MMA(1, 1, At, B1); PG8_BAR; PG8_SCHED;
;             PG8_LDB(B0, 1, 0); PG8_LDB(B1, 1, 1); PG8_SCHED; PG8_LDA(At, 1, 0); PG8_STAGE(PG8_SA(0, 1), a2 + hstep, voffA);
;             PG8_WAIT_V(8); PG8_WAIT_L(0); PG8_BAR; PG8_MMA(0, 0, At, B0); PG8_MMA(0, 1, At, B1); PG8_BAR; PG8_SCHED;
	v_mfma_f32_16x16x32_f16 v[66:69], v[126:129], v[176:179], v[66:69]
	v_mfma_f32_16x16x32_f16 v[62:65], v[142:145], v[176:179], v[62:65]
	v_mfma_f32_16x16x32_f16 v[50:53], v[126:129], v[188:191], v[50:53]
	v_mfma_f32_16x16x32_f16 v[46:49], v[142:145], v[188:191], v[46:49]
	v_mfma_f32_16x16x32_f16 v[34:37], v[126:129], v[196:199], v[34:37]
	v_mfma_f32_16x16x32_f16 v[30:33], v[142:145], v[196:199], v[30:33]
	v_mfma_f32_16x16x32_f16 v[18:21], v[126:129], v[204:207], v[18:21]
	v_mfma_f32_16x16x32_f16 v[10:13], v[142:145], v[204:207], v[10:13]
	v_mfma_f32_16x16x32_f16 v[66:69], v[138:141], v[184:187], v[66:69]
	v_mfma_f32_16x16x32_f16 v[62:65], v[146:149], v[184:187], v[62:65]
	v_mfma_f32_16x16x32_f16 v[50:53], v[138:141], v[192:195], v[50:53]
	v_mfma_f32_16x16x32_f16 v[46:49], v[146:149], v[192:195], v[46:49]
	v_mfma_f32_16x16x32_f16 v[34:37], v[138:141], v[200:203], v[34:37]
	v_mfma_f32_16x16x32_f16 v[30:33], v[146:149], v[200:203], v[30:33]
	v_mfma_f32_16x16x32_f16 v[18:21], v[138:141], v[208:211], v[18:21]
	v_mfma_f32_16x16x32_f16 v[10:13], v[146:149], v[208:211], v[10:13]
	v_mfma_f32_16x16x32_f16 v[58:61], v[150:153], v[176:179], v[58:61]
	v_mfma_f32_16x16x32_f16 v[54:57], v[168:171], v[176:179], v[54:57]
	v_mfma_f32_16x16x32_f16 v[42:45], v[150:153], v[188:191], v[42:45]
	v_mfma_f32_16x16x32_f16 v[38:41], v[168:171], v[188:191], v[38:41]
	v_mfma_f32_16x16x32_f16 v[26:29], v[150:153], v[196:199], v[26:29]
	v_mfma_f32_16x16x32_f16 v[22:25], v[168:171], v[196:199], v[22:25]
	v_mfma_f32_16x16x32_f16 v[6:9], v[150:153], v[204:207], v[6:9]
	v_mfma_f32_16x16x32_f16 v[2:5], v[168:171], v[204:207], v[2:5]
	v_mfma_f32_16x16x32_f16 v[58:61], v[154:157], v[184:187], v[58:61]
	v_mfma_f32_16x16x32_f16 v[54:57], v[172:175], v[184:187], v[54:57]
	v_mfma_f32_16x16x32_f16 v[42:45], v[154:157], v[192:195], v[42:45]
	v_mfma_f32_16x16x32_f16 v[38:41], v[172:175], v[192:195], v[38:41]
	v_mfma_f32_16x16x32_f16 v[26:29], v[154:157], v[200:203], v[26:29]
	v_mfma_f32_16x16x32_f16 v[22:25], v[172:175], v[200:203], v[22:25]
	v_mfma_f32_16x16x32_f16 v[6:9], v[154:157], v[208:211], v[6:9]
	v_mfma_f32_16x16x32_f16 v[2:5], v[172:175], v[208:211], v[2:5]
	s_barrier
	s_add_i32 s92, 0, 0x18000
	v_add_u32_e32 v1, s92, v180
	s_add_i32 s93, 0, 0x1c000
	ds_read_b128 v[126:129], v1
	ds_read_b128 v[138:141], v1 offset:1024
	ds_read_b128 v[142:145], v1 offset:2048
	ds_read_b128 v[146:149], v1 offset:3072
	v_add_u32_e32 v1, s93, v180
	ds_read_b128 v[150:153], v1
	ds_read_b128 v[154:157], v1 offset:1024
	ds_read_b128 v[168:171], v1 offset:2048
	ds_read_b128 v[172:175], v1 offset:3072
	s_add_u32 s12, s24, 0x40000
	s_addc_u32 s13, s25, 0
	s_mov_b32 m0, s49
	v_lshl_add_u64 v[222:223], s[12:13], 0, v[162:163]
	ds_read_b128 v[176:179], v182 offset:32768
	ds_read_b128 v[184:187], v182 offset:33792
	ds_read_b128 v[188:191], v182 offset:34816
	ds_read_b128 v[192:195], v182 offset:35840
	ds_read_b128 v[196:199], v182 offset:36864
	ds_read_b128 v[200:203], v182 offset:37888
	ds_read_b128 v[204:207], v182 offset:38912
	ds_read_b128 v[208:211], v182 offset:39936
	global_load_lds_dwordx4 v[222:223], off
	v_lshl_add_u64 v[222:223], s[12:13], 0, v[158:159]
	s_mov_b32 m0, s71
	s_nop 0
	global_load_lds_dwordx4 v[222:223], off
	s_waitcnt vmcnt(8)
	s_waitcnt lgkmcnt(0)
	s_barrier
	v_mfma_f32_16x16x32_f16 v[134:137], v[126:129], v[176:179], v[134:137]
	v_mfma_f32_16x16x32_f16 v[130:133], v[142:145], v[176:179], v[130:133]
	v_mfma_f32_16x16x32_f16 v[114:117], v[126:129], v[188:191], v[114:117]
	v_mfma_f32_16x16x32_f16 v[110:113], v[142:145], v[188:191], v[110:113]
	v_mfma_f32_16x16x32_f16 v[98:101], v[126:129], v[196:199], v[98:101]
	v_mfma_f32_16x16x32_f16 v[94:97], v[142:145], v[196:199], v[94:97]
	v_mfma_f32_16x16x32_f16 v[82:85], v[126:129], v[204:207], v[82:85]
	v_mfma_f32_16x16x32_f16 v[78:81], v[142:145], v[204:207], v[78:81]
	v_mfma_f32_16x16x32_f16 v[134:137], v[138:141], v[184:187], v[134:137]
	v_mfma_f32_16x16x32_f16 v[130:133], v[146:149], v[184:187], v[130:133]
	v_mfma_f32_16x16x32_f16 v[114:117], v[138:141], v[192:195], v[114:117]
	v_mfma_f32_16x16x32_f16 v[110:113], v[146:149], v[192:195], v[110:113]
	v_mfma_f32_16x16x32_f16 v[98:101], v[138:141], v[200:203], v[98:101]
	v_mfma_f32_16x16x32_f16 v[94:97], v[146:149], v[200:203], v[94:97]
	v_mfma_f32_16x16x32_f16 v[82:85], v[138:141], v[208:211], v[82:85]
	v_mfma_f32_16x16x32_f16 v[78:81], v[146:149], v[208:211], v[78:81]
	v_mfma_f32_16x16x32_f16 v[122:125], v[150:153], v[176:179], v[122:125]
	v_mfma_f32_16x16x32_f16 v[118:121], v[168:171], v[176:179], v[118:121]
	v_mfma_f32_16x16x32_f16 v[106:109], v[150:153], v[188:191], v[106:109]
	v_mfma_f32_16x16x32_f16 v[102:105], v[168:171], v[188:191], v[102:105]
	v_mfma_f32_16x16x32_f16 v[90:93], v[150:153], v[196:199], v[90:93]
	v_mfma_f32_16x16x32_f16 v[86:89], v[168:171], v[196:199], v[86:89]
	v_mfma_f32_16x16x32_f16 v[74:77], v[150:153], v[204:207], v[74:77]
	v_mfma_f32_16x16x32_f16 v[70:73], v[168:171], v[204:207], v[70:73]
	v_mfma_f32_16x16x32_f16 v[122:125], v[154:157], v[184:187], v[122:125]
	v_mfma_f32_16x16x32_f16 v[118:121], v[172:175], v[184:187], v[118:121]
	v_mfma_f32_16x16x32_f16 v[106:109], v[154:157], v[192:195], v[106:109]
	v_mfma_f32_16x16x32_f16 v[102:105], v[172:175], v[192:195], v[102:105]
	v_mfma_f32_16x16x32_f16 v[90:93], v[154:157], v[200:203], v[90:93]
	v_mfma_f32_16x16x32_f16 v[86:89], v[172:175], v[200:203], v[86:89]
	v_mfma_f32_16x16x32_f16 v[74:77], v[154:157], v[208:211], v[74:77]
	v_mfma_f32_16x16x32_f16 v[70:73], v[172:175], v[208:211], v[70:73]
	s_barrier
; #define PG8_STAGE(bufoff, gbase, voff) do { _Pragma("unroll") for (int _i = 0; _i < 2; ++_i) \
;         __builtin_amdgcn_global_load_lds((const unsigned*)((const char*)(gbase) + (voff)[_i]), (PG8_LAS unsigned*)(lds + (bufoff) + ldsw + _i * 8192), 16, 0, 0); } while (0)
; #define PG8_LDA(dst, b, h) do { _Pragma("unroll") for (int m = 0; m < 4; ++m) _Pragma("unroll") for (int k = 0; k < 2; ++k) dst[m][k] = *(const PG8_LAS bf16x8*)(lds + PG8_SA(b, h) + aoff + m * 2048 + k * 1024); } while (0)
; #define PG8_WAIT_V(n) asm volatile("s_waitcnt vmcnt(" #n ")" ::: "memory")
; template <class Epi, class Sched, bool ALIGN_EPI = false, bool SP2 = false>
; __device__ __forceinline__ void gemm_phase(PG8_LAS unsigned char* lds, const Gemm g, const Sched& S, const Epi& E) {
;     ...
;             PG8_LDA(At, 1, 1); PG8_STAGE(PG8_SB(1, 0), b3, voffB); PG8_STAGE(PG8_SB(1, 1), b3 + hstep, voffB); PG8_STAGE(PG8_SA(1, 0), a3, voffA);
;             PG8_WAIT_V(8); PG8_WAIT_L(0); PG8_BAR; PG8_MMA(1, 0, At, B0); PG8_MMA(1, 1, At, B1); PG8_BAR; PG8_SCHED;
;             } else {
;             PG8_LDB(B0, 0, 0); PG8_SCHED; PG8_LDA(At, 0, 0); PG8_STAGE(PG8_SA(1, 1), a1 + hstep, voffA);
;             PG8_WAIT_L(8); PG8_BAR; PG8_WAIT_L(0); PG8_MMA(0, 0, At, B0); PG8_BAR; PG8_SCHED;
;             PG8_LDB(B1, 0, 1); PG8_STAGE(PG8_SB(0, 0), b2, voffB);
;             PG8_BAR; PG8_WAIT_L(0); PG8_MMA(0, 1, At, B1); PG8_BAR;
;             PG8_LDA(At, 0, 1); PG8_STAGE(PG8_SA(0, 0), a2, voffA);
;             PG8_BAR; PG8_WAIT_L(0); PG8_MMA(1, 0, At, B0); PG8_BAR; PG8_SCHED;
;             PG8_STAGE(PG8_SB(0, 1), b2 + hstep, voffB);
;             PG8_WAIT_V(6); PG8_BAR; PG8_MMA(1, 1, At, B1); PG8_BAR;
;             PG8_LDB(B0, 1, 0); PG8_SCHED; PG8_LDA(At, 1, 0); PG8_STAGE(PG8_SA(0, 1), a2 + hstep, voffA);
;             PG8_WAIT_L(8); PG8_BAR; PG8_WAIT_L(0); PG8_MMA(0, 0, At, B0); PG8_BAR; PG8_SCHED;
;             PG8_LDB(B1, 1, 1); PG8_STAGE(PG8_SB(1, 0), b3, voffB);
;             PG8_BAR; PG8_WAIT_L(0); PG8_MMA(0, 1, At, B1); PG8_BAR;
;             PG8_LDA(At, 1, 1); PG8_STAGE(PG8_SA(1, 0), a3, voffA);
;             PG8_BAR; PG8_WAIT_L(0); PG8_MMA(1, 0, At, B0); PG8_BAR; PG8_SCHED;
;             PG8_STAGE(PG8_SB(1, 1), b3 + hstep, voffB);
;             PG8_WAIT_V(6); PG8_BAR; PG8_MMA(1, 1, At, B1); PG8_BAR;
;             }
;         }
;         if constexpr (ALIGN_EPI) { if (wr == 0) PG8_BAR; }
	s_add_i32 s12, s92, s11
	v_lshl_add_u64 v[212:213], v[212:213], 0, s[34:35]
	s_mov_b32 m0, s12
	ds_read_b128 v[176:179], v182 offset:49152
	ds_read_b128 v[184:187], v182 offset:50176
	ds_read_b128 v[188:191], v182 offset:51200
	ds_read_b128 v[192:195], v182 offset:52224
	ds_read_b128 v[196:199], v182 offset:53248
	ds_read_b128 v[200:203], v182 offset:54272
	ds_read_b128 v[204:207], v182 offset:55296
	ds_read_b128 v[208:211], v182 offset:56320
	global_load_lds_dwordx4 v[212:213], off
	s_add_i32 m0, s12, 0x2000
	s_add_u32 s12, s22, 0x40080
	v_lshl_add_u64 v[212:213], v[214:215], 0, s[34:35]
	s_addc_u32 s13, s23, 0
	s_add_i32 s22, s93, s11
	global_load_lds_dwordx4 v[212:213], off
	v_lshl_add_u64 v[212:213], s[12:13], 0, v[160:161]
	s_mov_b32 m0, s22
	s_nop 0
	global_load_lds_dwordx4 v[212:213], off
	v_lshl_add_u64 v[212:213], s[12:13], 0, v[14:15]
	s_add_i32 m0, s22, 0x2000
	s_nop 0
	global_load_lds_dwordx4 v[212:213], off
	v_lshl_add_u64 v[212:213], v[218:219], 0, s[34:35]
	s_mov_b32 m0, s73
	s_nop 0
	global_load_lds_dwordx4 v[212:213], off
	v_lshl_add_u64 v[212:213], v[220:221], 0, s[34:35]
	s_mov_b32 m0, s76
	s_nop 0
	global_load_lds_dwordx4 v[212:213], off
	s_waitcnt vmcnt(8)
	s_waitcnt lgkmcnt(0)
	s_barrier
	v_mfma_f32_16x16x32_f16 v[66:69], v[126:129], v[176:179], v[66:69]
	v_mfma_f32_16x16x32_f16 v[62:65], v[142:145], v[176:179], v[62:65]
	v_mfma_f32_16x16x32_f16 v[50:53], v[126:129], v[188:191], v[50:53]
	v_mfma_f32_16x16x32_f16 v[46:49], v[142:145], v[188:191], v[46:49]
	v_mfma_f32_16x16x32_f16 v[34:37], v[126:129], v[196:199], v[34:37]
	v_mfma_f32_16x16x32_f16 v[30:33], v[142:145], v[196:199], v[30:33]
	v_mfma_f32_16x16x32_f16 v[18:21], v[126:129], v[204:207], v[18:21]
	v_mfma_f32_16x16x32_f16 v[10:13], v[142:145], v[204:207], v[10:13]
	v_mfma_f32_16x16x32_f16 v[66:69], v[138:141], v[184:187], v[66:69]
	v_mfma_f32_16x16x32_f16 v[62:65], v[146:149], v[184:187], v[62:65]
	v_mfma_f32_16x16x32_f16 v[50:53], v[138:141], v[192:195], v[50:53]
	v_mfma_f32_16x16x32_f16 v[46:49], v[146:149], v[192:195], v[46:49]
	v_mfma_f32_16x16x32_f16 v[34:37], v[138:141], v[200:203], v[34:37]
	v_mfma_f32_16x16x32_f16 v[30:33], v[146:149], v[200:203], v[30:33]
	v_mfma_f32_16x16x32_f16 v[18:21], v[138:141], v[208:211], v[18:21]
	v_mfma_f32_16x16x32_f16 v[10:13], v[146:149], v[208:211], v[10:13]
	v_mfma_f32_16x16x32_f16 v[58:61], v[150:153], v[176:179], v[58:61]
	v_mfma_f32_16x16x32_f16 v[54:57], v[168:171], v[176:179], v[54:57]
	v_mfma_f32_16x16x32_f16 v[42:45], v[150:153], v[188:191], v[42:45]
	v_mfma_f32_16x16x32_f16 v[38:41], v[168:171], v[188:191], v[38:41]
	v_mfma_f32_16x16x32_f16 v[26:29], v[150:153], v[196:199], v[26:29]
	v_mfma_f32_16x16x32_f16 v[22:25], v[168:171], v[196:199], v[22:25]
	v_mfma_f32_16x16x32_f16 v[6:9], v[150:153], v[204:207], v[6:9]
	v_mfma_f32_16x16x32_f16 v[2:5], v[168:171], v[204:207], v[2:5]
	v_mfma_f32_16x16x32_f16 v[58:61], v[154:157], v[184:187], v[58:61]
	v_mfma_f32_16x16x32_f16 v[54:57], v[172:175], v[184:187], v[54:57]
	v_mfma_f32_16x16x32_f16 v[42:45], v[154:157], v[192:195], v[42:45]
	v_mfma_f32_16x16x32_f16 v[38:41], v[172:175], v[192:195], v[38:41]
	v_mfma_f32_16x16x32_f16 v[26:29], v[154:157], v[200:203], v[26:29]
	v_mfma_f32_16x16x32_f16 v[22:25], v[172:175], v[200:203], v[22:25]
	v_mfma_f32_16x16x32_f16 v[6:9], v[154:157], v[208:211], v[6:9]
	v_mfma_f32_16x16x32_f16 v[2:5], v[172:175], v[208:211], v[2:5]
	s_barrier
	s_add_i32 vcc_hi, vcc_hi, 2
	s_add_u32 s82, s82, 0x100
	s_addc_u32 s83, s83, 0
	s_add_u32 s58, s58, 0x100
	s_addc_u32 vcc_lo, vcc_lo, 0
	s_cmp_gt_u32 vcc_hi, 13
	s_cbranch_scc0 .LBB0_824
	s_and_b64 vcc, exec, s[14:15]
	s_cbranch_vccz .LBB0_827
	s_barrier

; #define PG8_STAGE(bufoff, gbase, voff) do { _Pragma("unroll") for (int _i = 0; _i < 2; ++_i) \
;         __builtin_amdgcn_global_load_lds((const unsigned*)((const char*)(gbase) + (voff)[_i]), (PG8_LAS unsigned*)(lds + (bufoff) + ldsw + _i * 8192), 16, 0, 0); } while (0)
; #define PG8_LDA(dst, b, h) do { _Pragma("unroll") for (int m = 0; m < 4; ++m) _Pragma("unroll") for (int k = 0; k < 2; ++k) dst[m][k] = *(const PG8_LAS bf16x8*)(lds + PG8_SA(b, h) + aoff + m * 2048 + k * 1024); } while (0)
; #define PG8_LDB(dst, b, h) do { _Pragma("unroll") for (int n = 0; n < 2; ++n) _Pragma("unroll") for (int k = 0; k < 2; ++k) dst[n][k] = *(const PG8_LAS bf16x8*)(lds + PG8_SB(b, h) + boff + n * 2048 + k * 1024); } while (0)
; #define PG8_MMA(ai, bj, At, Bt) do { __builtin_amdgcn_s_setprio(1); _Pragma("unroll") for (int m = 0; m < 4; ++m) _Pragma("unroll") for (int n = 0; n < 2; ++n) _Pragma("unroll") for (int k = 0; k < 2; ++k) \
;         acc[ai][bj][m][n] = __builtin_amdgcn_mfma_f32_16x16x32_f16(Bt[n][k], At[m][k], acc[ai][bj][m][n], 0, 0, 0); __builtin_amdgcn_s_setprio(0); } while (0)
; #define PG8_WAIT_V(n) asm volatile("s_waitcnt vmcnt(" #n ")" ::: "memory")
; #define PG8_WAIT_L(n) asm volatile("s_waitcnt lgkmcnt(" #n ")" ::: "memory")
; #define PG8_BAR __builtin_amdgcn_s_barrier()
; #define PG8_SCHED __builtin_amdgcn_sched_barrier(0)
; template <class Epi, class Sched, bool ALIGN_EPI = false, bool SP2 = false>
; __device__ __forceinline__ void gemm_phase(PG8_LAS unsigned char* lds, const Gemm g, const Sched& S, const Epi& E) {
;     ...
;         for (int t = 0; t < nt; t += 2) {
;             const bool last = (t == nt - 2);
;             const char* a1 = cA + (size_t)(t + 1) * kstep;
;             const char* a2 = last ? nA : cA + (size_t)(t + 2) * kstep; const char* b2 = last ? nB : cB + (size_t)(t + 2) * kstep;
;             const char* a3 = a2 + kstep; const char* b3 = b2 + kstep;
;             if (last && has_next) S.a_ready(nxt);
;             if constexpr (SP2) {
;             PG8_LDB(B0, 0, 0); PG8_LDB(B1, 0, 1); PG8_SCHED; PG8_LDA(At, 0, 0); PG8_STAGE(PG8_SA(1, 1), a1 + hstep, voffA);
;             PG8_WAIT_V(8); PG8_WAIT_L(0); PG8_BAR; PG8_MMA(0, 0, At, B0); PG8_MMA(0, 1, At, B1); PG8_BAR; PG8_SCHED;
;             PG8_LDA(At, 0, 1); PG8_STAGE(PG8_SB(0, 0), b2, voffB); PG8_STAGE(PG8_SB(0, 1), b2 + hstep, voffB); PG8_STAGE(PG8_SA(0, 0), a2, voffA);
.LBB0_986:
	s_add_u32 s13, s50, 0xfffc0080
	s_addc_u32 s22, s51, -1
	s_add_i32 s83, 0, 0x10000
	s_cmp_eq_u32 s12, 12
	s_cselect_b32 s25, s39, s22
	s_cselect_b32 s24, s73, s13
	s_cselect_b32 s23, s17, s82
	s_cselect_b32 s22, s76, s77
	s_add_i32 s13, 0, 0x14000
	v_add_u32_e32 v146, s83, v17
	v_add_u32_e32 v162, s13, v17
	ds_read_b128 v[134:137], v146
	ds_read_b128 v[138:141], v146 offset:1024
	ds_read_b128 v[142:145], v146 offset:2048
	ds_read_b128 v[146:149], v146 offset:3072
	ds_read_b128 v[150:153], v162
	ds_read_b128 v[154:157], v162 offset:1024
	ds_read_b128 v[158:161], v162 offset:2048
	ds_read_b128 v[162:165], v162 offset:3072
	v_lshl_add_u64 v[180:181], s[50:51], 0, v[172:173]
	s_add_i32 m0, s20, 0xc000
	ds_read_b128 v[176:179], v184
	ds_read_b128 v[186:189], v184 offset:1024
	ds_read_b128 v[190:193], v184 offset:2048
	ds_read_b128 v[194:197], v184 offset:3072
	ds_read_b128 v[198:201], v184 offset:4096
	ds_read_b128 v[202:205], v184 offset:5120
	ds_read_b128 v[206:209], v184 offset:6144
	ds_read_b128 v[210:213], v184 offset:7168
	global_load_lds_dwordx4 v[180:181], off
	v_lshl_add_u64 v[180:181], s[50:51], 0, v[174:175]
	s_add_i32 m0, s20, 0xe000
	s_nop 0
	global_load_lds_dwordx4 v[180:181], off
	s_waitcnt vmcnt(8)
	s_waitcnt lgkmcnt(0)
	s_barrier
	v_mfma_f32_16x16x32_f16 v[130:133], v[134:137], v[176:179], v[130:133]
	v_mfma_f32_16x16x32_f16 v[126:129], v[142:145], v[176:179], v[126:129]
	v_mfma_f32_16x16x32_f16 v[114:117], v[134:137], v[190:193], v[114:117]
	v_mfma_f32_16x16x32_f16 v[110:113], v[142:145], v[190:193], v[110:113]
	v_mfma_f32_16x16x32_f16 v[98:101], v[134:137], v[198:201], v[98:101]
	v_mfma_f32_16x16x32_f16 v[94:97], v[142:145], v[198:201], v[94:97]
	v_mfma_f32_16x16x32_f16 v[82:85], v[134:137], v[206:209], v[82:85]
	v_mfma_f32_16x16x32_f16 v[78:81], v[142:145], v[206:209], v[78:81]
	v_mfma_f32_16x16x32_f16 v[130:133], v[138:141], v[186:189], v[130:133]
	v_mfma_f32_16x16x32_f16 v[126:129], v[146:149], v[186:189], v[126:129]
	v_mfma_f32_16x16x32_f16 v[114:117], v[138:141], v[194:197], v[114:117]
	v_mfma_f32_16x16x32_f16 v[110:113], v[146:149], v[194:197], v[110:113]
	v_mfma_f32_16x16x32_f16 v[98:101], v[138:141], v[202:205], v[98:101]
	v_mfma_f32_16x16x32_f16 v[94:97], v[146:149], v[202:205], v[94:97]
	v_mfma_f32_16x16x32_f16 v[82:85], v[138:141], v[210:213], v[82:85]
	v_mfma_f32_16x16x32_f16 v[78:81], v[146:149], v[210:213], v[78:81]
	v_mfma_f32_16x16x32_f16 v[122:125], v[150:153], v[176:179], v[122:125]
	v_mfma_f32_16x16x32_f16 v[118:121], v[158:161], v[176:179], v[118:121]
	v_mfma_f32_16x16x32_f16 v[106:109], v[150:153], v[190:193], v[106:109]
	v_mfma_f32_16x16x32_f16 v[102:105], v[158:161], v[190:193], v[102:105]
	v_mfma_f32_16x16x32_f16 v[90:93], v[150:153], v[198:201], v[90:93]
	v_mfma_f32_16x16x32_f16 v[86:89], v[158:161], v[198:201], v[86:89]
	v_mfma_f32_16x16x32_f16 v[74:77], v[150:153], v[206:209], v[74:77]
	v_mfma_f32_16x16x32_f16 v[70:73], v[158:161], v[206:209], v[70:73]
	v_mfma_f32_16x16x32_f16 v[122:125], v[154:157], v[186:189], v[122:125]
	v_mfma_f32_16x16x32_f16 v[118:121], v[162:165], v[186:189], v[118:121]
	v_mfma_f32_16x16x32_f16 v[106:109], v[154:157], v[194:197], v[106:109]
	v_mfma_f32_16x16x32_f16 v[102:105], v[162:165], v[194:197], v[102:105]
	v_mfma_f32_16x16x32_f16 v[90:93], v[154:157], v[202:205], v[90:93]
	v_mfma_f32_16x16x32_f16 v[86:89], v[162:165], v[202:205], v[86:89]
	v_mfma_f32_16x16x32_f16 v[74:77], v[154:157], v[210:213], v[74:77]
	v_mfma_f32_16x16x32_f16 v[70:73], v[162:165], v[210:213], v[70:73]
	s_barrier
	s_add_i32 s83, s83, s5
	v_lshl_add_u64 v[180:181], s[22:23], 0, v[168:169]
	s_mov_b32 m0, s83
	ds_read_b128 v[176:179], v184 offset:16384
	ds_read_b128 v[186:189], v184 offset:17408
	ds_read_b128 v[190:193], v184 offset:18432
	ds_read_b128 v[194:197], v184 offset:19456
	ds_read_b128 v[198:201], v184 offset:20480
	ds_read_b128 v[202:205], v184 offset:21504
	ds_read_b128 v[206:209], v184 offset:22528
	ds_read_b128 v[210:213], v184 offset:23552
	global_load_lds_dwordx4 v[180:181], off
	s_add_i32 m0, s83, 0x2000
	s_add_u32 s92, s22, 0x40000
	v_lshl_add_u64 v[214:215], s[22:23], 0, v[14:15]
	s_addc_u32 s93, s23, 0
	s_add_i32 s13, s13, s5
	global_load_lds_dwordx4 v[214:215], off
	v_lshl_add_u64 v[218:219], s[92:93], 0, v[168:169]
	s_mov_b32 m0, s13
	v_lshl_add_u64 v[220:221], s[24:25], 0, v[166:167]
	global_load_lds_dwordx4 v[218:219], off
	v_lshl_add_u64 v[218:219], s[92:93], 0, v[14:15]
	s_add_i32 m0, s13, 0x2000
	s_nop 0
	global_load_lds_dwordx4 v[218:219], off
	v_lshl_add_u64 v[218:219], s[24:25], 0, v[170:171]
	s_mov_b32 m0, s20
	s_nop 0
	global_load_lds_dwordx4 v[218:219], off
	s_mov_b32 m0, s26
	s_nop 0
	global_load_lds_dwordx4 v[220:221], off
	s_waitcnt vmcnt(8)
	s_waitcnt lgkmcnt(0)
	s_barrier
; #define PG8_STAGE(bufoff, gbase, voff) do { _Pragma("unroll") for (int _i = 0; _i < 2; ++_i) \
;         __builtin_amdgcn_global_load_lds((const unsigned*)((const char*)(gbase) + (voff)[_i]), (PG8_LAS unsigned*)(lds + (bufoff) + ldsw + _i * 8192), 16, 0, 0); } while (0)
; #define PG8_LDA(dst, b, h) do { _Pragma("unroll") for (int m = 0; m < 4; ++m) _Pragma("unroll") for (int k = 0; k < 2; ++k) dst[m][k] = *(const PG8_LAS bf16x8*)(lds + PG8_SA(b, h) + aoff + m * 2048 + k * 1024); } while (0)
; #define PG8_LDB(dst, b, h) do { _Pragma("unroll") for (int n = 0; n < 2; ++n) _Pragma("unroll") for (int k = 0; k < 2; ++k) dst[n][k] = *(const PG8_LAS bf16x8*)(lds + PG8_SB(b, h) + boff + n * 2048 + k * 1024); } while (0)
; #define PG8_MMA(ai, bj, At, Bt) do { __builtin_amdgcn_s_setprio(1); _Pragma("unroll") for (int m = 0; m < 4; ++m) _Pragma("unroll") for (int n = 0; n < 2; ++n) _Pragma("unroll") for (int k = 0; k < 2; ++k) \
;         acc[ai][bj][m][n] = __builtin_amdgcn_mfma_f32_16x16x32_f16(Bt[n][k], At[m][k], acc[ai][bj][m][n], 0, 0, 0); __builtin_amdgcn_s_setprio(0); } while (0)
; #define PG8_WAIT_V(n) asm volatile("s_waitcnt vmcnt(" #n ")" ::: "memory")
; #define PG8_WAIT_L(n) asm volatile("s_waitcnt lgkmcnt(" #n ")" ::: "memory")
; #define PG8_BAR __builtin_amdgcn_s_barrier()
; #define PG8_SCHED __builtin_amdgcn_sched_barrier(0)
; template <class Epi, class Sched, bool ALIGN_EPI = false, bool SP2 = false>
; __device__ __forceinline__ void gemm_phase(PG8_LAS unsigned char* lds, const Gemm g, const Sched& S, const Epi& E) {
;     ...
;             PG8_LDA(At, 0, 1); PG8_STAGE(PG8_SB(0, 0), b2, voffB); PG8_STAGE(PG8_SB(0, 1), b2 + hstep, voffB); PG8_STAGE(PG8_SA(0, 0), a2, voffA);
;             PG8_WAIT_V(8); PG8_WAIT_L(0); PG8_BAR; PG8_MMA(1, 0, At, B0); PG8_MMA(1, 1, At, B1); PG8_BAR; PG8_SCHED;
;             PG8_LDB(B0, 1, 0); PG8_LDB(B1, 1, 1); PG8_SCHED; PG8_LDA(At, 1, 0); PG8_STAGE(PG8_SA(0, 1), a2 + hstep, voffA);
;             PG8_WAIT_V(8); PG8_WAIT_L(0); PG8_BAR; PG8_MMA(0, 0, At, B0); PG8_MMA(0, 1, At, B1); PG8_BAR; PG8_SCHED;
	v_mfma_f32_16x16x32_f16 v[66:69], v[134:137], v[176:179], v[66:69]
	v_mfma_f32_16x16x32_f16 v[62:65], v[142:145], v[176:179], v[62:65]
	v_mfma_f32_16x16x32_f16 v[50:53], v[134:137], v[190:193], v[50:53]
	v_mfma_f32_16x16x32_f16 v[46:49], v[142:145], v[190:193], v[46:49]
	v_mfma_f32_16x16x32_f16 v[34:37], v[134:137], v[198:201], v[34:37]
	v_mfma_f32_16x16x32_f16 v[30:33], v[142:145], v[198:201], v[30:33]
	v_mfma_f32_16x16x32_f16 v[18:21], v[134:137], v[206:209], v[18:21]
	v_mfma_f32_16x16x32_f16 v[10:13], v[142:145], v[206:209], v[10:13]
	v_mfma_f32_16x16x32_f16 v[66:69], v[138:141], v[186:189], v[66:69]
	v_mfma_f32_16x16x32_f16 v[62:65], v[146:149], v[186:189], v[62:65]
	v_mfma_f32_16x16x32_f16 v[50:53], v[138:141], v[194:197], v[50:53]
	v_mfma_f32_16x16x32_f16 v[46:49], v[146:149], v[194:197], v[46:49]
	v_mfma_f32_16x16x32_f16 v[34:37], v[138:141], v[202:205], v[34:37]
	v_mfma_f32_16x16x32_f16 v[30:33], v[146:149], v[202:205], v[30:33]
	v_mfma_f32_16x16x32_f16 v[18:21], v[138:141], v[210:213], v[18:21]
	v_mfma_f32_16x16x32_f16 v[10:13], v[146:149], v[210:213], v[10:13]
	v_mfma_f32_16x16x32_f16 v[58:61], v[150:153], v[176:179], v[58:61]
	v_mfma_f32_16x16x32_f16 v[54:57], v[158:161], v[176:179], v[54:57]
	v_mfma_f32_16x16x32_f16 v[42:45], v[150:153], v[190:193], v[42:45]
	v_mfma_f32_16x16x32_f16 v[38:41], v[158:161], v[190:193], v[38:41]
	v_mfma_f32_16x16x32_f16 v[26:29], v[150:153], v[198:201], v[26:29]
	v_mfma_f32_16x16x32_f16 v[22:25], v[158:161], v[198:201], v[22:25]
	v_mfma_f32_16x16x32_f16 v[6:9], v[150:153], v[206:209], v[6:9]
	v_mfma_f32_16x16x32_f16 v[2:5], v[158:161], v[206:209], v[2:5]
	v_mfma_f32_16x16x32_f16 v[58:61], v[154:157], v[186:189], v[58:61]
	v_mfma_f32_16x16x32_f16 v[54:57], v[162:165], v[186:189], v[54:57]
	v_mfma_f32_16x16x32_f16 v[42:45], v[154:157], v[194:197], v[42:45]
	v_mfma_f32_16x16x32_f16 v[38:41], v[162:165], v[194:197], v[38:41]
	v_mfma_f32_16x16x32_f16 v[26:29], v[154:157], v[202:205], v[26:29]
	v_mfma_f32_16x16x32_f16 v[22:25], v[162:165], v[202:205], v[22:25]
	v_mfma_f32_16x16x32_f16 v[6:9], v[154:157], v[210:213], v[6:9]
	v_mfma_f32_16x16x32_f16 v[2:5], v[162:165], v[210:213], v[2:5]
	s_barrier
	s_add_i32 s13, 0, 0x18000
	s_add_i32 s83, 0, 0x1c000
	v_add_u32_e32 v146, s13, v17
	v_add_u32_e32 v162, s83, v17
	ds_read_b128 v[134:137], v146
	ds_read_b128 v[138:141], v146 offset:1024
	ds_read_b128 v[142:145], v146 offset:2048
	ds_read_b128 v[146:149], v146 offset:3072
	ds_read_b128 v[150:153], v162
	ds_read_b128 v[154:157], v162 offset:1024
	ds_read_b128 v[158:161], v162 offset:2048
	ds_read_b128 v[162:165], v162 offset:3072
	s_add_u32 s24, s24, 0x40000
	s_addc_u32 s25, s25, 0
	s_mov_b32 m0, s27
	v_lshl_add_u64 v[222:223], s[24:25], 0, v[170:171]
	ds_read_b128 v[176:179], v184 offset:32768
	ds_read_b128 v[186:189], v184 offset:33792
	ds_read_b128 v[190:193], v184 offset:34816
	ds_read_b128 v[194:197], v184 offset:35840
	ds_read_b128 v[198:201], v184 offset:36864
	ds_read_b128 v[202:205], v184 offset:37888
	ds_read_b128 v[206:209], v184 offset:38912
	ds_read_b128 v[210:213], v184 offset:39936
	global_load_lds_dwordx4 v[222:223], off
	v_lshl_add_u64 v[222:223], s[24:25], 0, v[166:167]
	s_mov_b32 m0, s28
	s_nop 0
	global_load_lds_dwordx4 v[222:223], off
	s_waitcnt vmcnt(8)
	s_waitcnt lgkmcnt(0)
	s_barrier
	v_mfma_f32_16x16x32_f16 v[130:133], v[134:137], v[176:179], v[130:133]
	v_mfma_f32_16x16x32_f16 v[126:129], v[142:145], v[176:179], v[126:129]
	v_mfma_f32_16x16x32_f16 v[114:117], v[134:137], v[190:193], v[114:117]
	v_mfma_f32_16x16x32_f16 v[110:113], v[142:145], v[190:193], v[110:113]
	v_mfma_f32_16x16x32_f16 v[98:101], v[134:137], v[198:201], v[98:101]
	v_mfma_f32_16x16x32_f16 v[94:97], v[142:145], v[198:201], v[94:97]
	v_mfma_f32_16x16x32_f16 v[82:85], v[134:137], v[206:209], v[82:85]
	v_mfma_f32_16x16x32_f16 v[78:81], v[142:145], v[206:209], v[78:81]
	v_mfma_f32_16x16x32_f16 v[130:133], v[138:141], v[186:189], v[130:133]
	v_mfma_f32_16x16x32_f16 v[126:129], v[146:149], v[186:189], v[126:129]
	v_mfma_f32_16x16x32_f16 v[114:117], v[138:141], v[194:197], v[114:117]
	v_mfma_f32_16x16x32_f16 v[110:113], v[146:149], v[194:197], v[110:113]
	v_mfma_f32_16x16x32_f16 v[98:101], v[138:141], v[202:205], v[98:101]
	v_mfma_f32_16x16x32_f16 v[94:97], v[146:149], v[202:205], v[94:97]
	v_mfma_f32_16x16x32_f16 v[82:85], v[138:141], v[210:213], v[82:85]
	v_mfma_f32_16x16x32_f16 v[78:81], v[146:149], v[210:213], v[78:81]
	v_mfma_f32_16x16x32_f16 v[122:125], v[150:153], v[176:179], v[122:125]
	v_mfma_f32_16x16x32_f16 v[118:121], v[158:161], v[176:179], v[118:121]
	v_mfma_f32_16x16x32_f16 v[106:109], v[150:153], v[190:193], v[106:109]
	v_mfma_f32_16x16x32_f16 v[102:105], v[158:161], v[190:193], v[102:105]
	v_mfma_f32_16x16x32_f16 v[90:93], v[150:153], v[198:201], v[90:93]
	v_mfma_f32_16x16x32_f16 v[86:89], v[158:161], v[198:201], v[86:89]
	v_mfma_f32_16x16x32_f16 v[74:77], v[150:153], v[206:209], v[74:77]
	v_mfma_f32_16x16x32_f16 v[70:73], v[158:161], v[206:209], v[70:73]
	v_mfma_f32_16x16x32_f16 v[122:125], v[154:157], v[186:189], v[122:125]
	v_mfma_f32_16x16x32_f16 v[118:121], v[162:165], v[186:189], v[118:121]
	v_mfma_f32_16x16x32_f16 v[106:109], v[154:157], v[194:197], v[106:109]
	v_mfma_f32_16x16x32_f16 v[102:105], v[162:165], v[194:197], v[102:105]
	v_mfma_f32_16x16x32_f16 v[90:93], v[154:157], v[202:205], v[90:93]
	v_mfma_f32_16x16x32_f16 v[86:89], v[162:165], v[202:205], v[86:89]
	v_mfma_f32_16x16x32_f16 v[74:77], v[154:157], v[210:213], v[74:77]
	v_mfma_f32_16x16x32_f16 v[70:73], v[162:165], v[210:213], v[70:73]
	s_barrier
; #define PG8_STAGE(bufoff, gbase, voff) do { _Pragma("unroll") for (int _i = 0; _i < 2; ++_i) \
;         __builtin_amdgcn_global_load_lds((const unsigned*)((const char*)(gbase) + (voff)[_i]), (PG8_LAS unsigned*)(lds + (bufoff) + ldsw + _i * 8192), 16, 0, 0); } while (0)
; #define PG8_LDA(dst, b, h) do { _Pragma("unroll") for (int m = 0; m < 4; ++m) _Pragma("unroll") for (int k = 0; k < 2; ++k) dst[m][k] = *(const PG8_LAS bf16x8*)(lds + PG8_SA(b, h) + aoff + m * 2048 + k * 1024); } while (0)
; #define PG8_WAIT_V(n) asm volatile("s_waitcnt vmcnt(" #n ")" ::: "memory")
; template <class Epi, class Sched, bool ALIGN_EPI = false, bool SP2 = false>
; __device__ __forceinline__ void gemm_phase(PG8_LAS unsigned char* lds, const Gemm g, const Sched& S, const Epi& E) {
;     ...
;             PG8_LDA(At, 1, 1); PG8_STAGE(PG8_SB(1, 0), b3, voffB); PG8_STAGE(PG8_SB(1, 1), b3 + hstep, voffB); PG8_STAGE(PG8_SA(1, 0), a3, voffA);
;             PG8_WAIT_V(8); PG8_WAIT_L(0); PG8_BAR; PG8_MMA(1, 0, At, B0); PG8_MMA(1, 1, At, B1); PG8_BAR; PG8_SCHED;
;             } else {
;             PG8_LDB(B0, 0, 0); PG8_SCHED; PG8_LDA(At, 0, 0); PG8_STAGE(PG8_SA(1, 1), a1 + hstep, voffA);
;             PG8_WAIT_L(8); PG8_BAR; PG8_WAIT_L(0); PG8_MMA(0, 0, At, B0); PG8_BAR; PG8_SCHED;
;             PG8_LDB(B1, 0, 1); PG8_STAGE(PG8_SB(0, 0), b2, voffB);
;             PG8_BAR; PG8_WAIT_L(0); PG8_MMA(0, 1, At, B1); PG8_BAR;
;             PG8_LDA(At, 0, 1); PG8_STAGE(PG8_SA(0, 0), a2, voffA);
;             PG8_BAR; PG8_WAIT_L(0); PG8_MMA(1, 0, At, B0); PG8_BAR; PG8_SCHED;
;             PG8_STAGE(PG8_SB(0, 1), b2 + hstep, voffB);
;             PG8_WAIT_V(6); PG8_BAR; PG8_MMA(1, 1, At, B1); PG8_BAR;
;             PG8_LDB(B0, 1, 0); PG8_SCHED; PG8_LDA(At, 1, 0); PG8_STAGE(PG8_SA(0, 1), a2 + hstep, voffA);
;             PG8_WAIT_L(8); PG8_BAR; PG8_WAIT_L(0); PG8_MMA(0, 0, At, B0); PG8_BAR; PG8_SCHED;
;             PG8_LDB(B1, 1, 1); PG8_STAGE(PG8_SB(1, 0), b3, voffB);
;             PG8_BAR; PG8_WAIT_L(0); PG8_MMA(0, 1, At, B1); PG8_BAR;
;             PG8_LDA(At, 1, 1); PG8_STAGE(PG8_SA(1, 0), a3, voffA);
;             PG8_BAR; PG8_WAIT_L(0); PG8_MMA(1, 0, At, B0); PG8_BAR; PG8_SCHED;
;             PG8_STAGE(PG8_SB(1, 1), b3 + hstep, voffB);
;             PG8_WAIT_V(6); PG8_BAR; PG8_MMA(1, 1, At, B1); PG8_BAR;
;             }
;         }
;         if constexpr (ALIGN_EPI) { if (wr == 0) PG8_BAR; }
	s_add_i32 s13, s13, s5
	v_lshl_add_u64 v[180:181], v[180:181], 0, s[34:35]
	s_mov_b32 m0, s13
	ds_read_b128 v[176:179], v184 offset:49152
	ds_read_b128 v[186:189], v184 offset:50176
	ds_read_b128 v[190:193], v184 offset:51200
	ds_read_b128 v[194:197], v184 offset:52224
	ds_read_b128 v[198:201], v184 offset:53248
	ds_read_b128 v[202:205], v184 offset:54272
	ds_read_b128 v[206:209], v184 offset:55296
	ds_read_b128 v[210:213], v184 offset:56320
	global_load_lds_dwordx4 v[180:181], off
	s_add_i32 m0, s13, 0x2000
	s_add_u32 s22, s22, 0x40080
	v_lshl_add_u64 v[180:181], v[214:215], 0, s[34:35]
	s_addc_u32 s23, s23, 0
	s_add_i32 s13, s83, s5
	global_load_lds_dwordx4 v[180:181], off
	v_lshl_add_u64 v[180:181], s[22:23], 0, v[168:169]
	s_mov_b32 m0, s13
	s_nop 0
	global_load_lds_dwordx4 v[180:181], off
	v_lshl_add_u64 v[180:181], s[22:23], 0, v[14:15]
	s_add_i32 m0, s13, 0x2000
	s_nop 0
	global_load_lds_dwordx4 v[180:181], off
	v_lshl_add_u64 v[180:181], v[218:219], 0, s[34:35]
	s_mov_b32 m0, s29
	s_nop 0
	global_load_lds_dwordx4 v[180:181], off
	v_lshl_add_u64 v[180:181], v[220:221], 0, s[34:35]
	s_mov_b32 m0, s33
	s_nop 0
	global_load_lds_dwordx4 v[180:181], off
	s_waitcnt vmcnt(8)
	s_waitcnt lgkmcnt(0)
	s_barrier
	v_mfma_f32_16x16x32_f16 v[66:69], v[134:137], v[176:179], v[66:69]
	v_mfma_f32_16x16x32_f16 v[62:65], v[142:145], v[176:179], v[62:65]
	v_mfma_f32_16x16x32_f16 v[50:53], v[134:137], v[190:193], v[50:53]
	v_mfma_f32_16x16x32_f16 v[46:49], v[142:145], v[190:193], v[46:49]
	v_mfma_f32_16x16x32_f16 v[34:37], v[134:137], v[198:201], v[34:37]
	v_mfma_f32_16x16x32_f16 v[30:33], v[142:145], v[198:201], v[30:33]
	v_mfma_f32_16x16x32_f16 v[18:21], v[134:137], v[206:209], v[18:21]
	v_mfma_f32_16x16x32_f16 v[10:13], v[142:145], v[206:209], v[10:13]
	v_mfma_f32_16x16x32_f16 v[66:69], v[138:141], v[186:189], v[66:69]
	v_mfma_f32_16x16x32_f16 v[62:65], v[146:149], v[186:189], v[62:65]
	v_mfma_f32_16x16x32_f16 v[50:53], v[138:141], v[194:197], v[50:53]
	v_mfma_f32_16x16x32_f16 v[46:49], v[146:149], v[194:197], v[46:49]
	v_mfma_f32_16x16x32_f16 v[34:37], v[138:141], v[202:205], v[34:37]
	v_mfma_f32_16x16x32_f16 v[30:33], v[146:149], v[202:205], v[30:33]
	v_mfma_f32_16x16x32_f16 v[18:21], v[138:141], v[210:213], v[18:21]
	v_mfma_f32_16x16x32_f16 v[10:13], v[146:149], v[210:213], v[10:13]
	v_mfma_f32_16x16x32_f16 v[58:61], v[150:153], v[176:179], v[58:61]
	v_mfma_f32_16x16x32_f16 v[54:57], v[158:161], v[176:179], v[54:57]
	v_mfma_f32_16x16x32_f16 v[42:45], v[150:153], v[190:193], v[42:45]
	v_mfma_f32_16x16x32_f16 v[38:41], v[158:161], v[190:193], v[38:41]
	v_mfma_f32_16x16x32_f16 v[26:29], v[150:153], v[198:201], v[26:29]
	v_mfma_f32_16x16x32_f16 v[22:25], v[158:161], v[198:201], v[22:25]
	v_mfma_f32_16x16x32_f16 v[6:9], v[150:153], v[206:209], v[6:9]
	v_mfma_f32_16x16x32_f16 v[2:5], v[158:161], v[206:209], v[2:5]
	v_mfma_f32_16x16x32_f16 v[58:61], v[154:157], v[186:189], v[58:61]
	v_mfma_f32_16x16x32_f16 v[54:57], v[162:165], v[186:189], v[54:57]
	v_mfma_f32_16x16x32_f16 v[42:45], v[154:157], v[194:197], v[42:45]
	v_mfma_f32_16x16x32_f16 v[38:41], v[162:165], v[194:197], v[38:41]
	v_mfma_f32_16x16x32_f16 v[26:29], v[154:157], v[202:205], v[26:29]
	v_mfma_f32_16x16x32_f16 v[22:25], v[162:165], v[202:205], v[22:25]
	v_mfma_f32_16x16x32_f16 v[6:9], v[154:157], v[210:213], v[6:9]
	v_mfma_f32_16x16x32_f16 v[2:5], v[162:165], v[210:213], v[2:5]
	s_barrier
	s_add_i32 s12, s12, 2
	s_add_u32 s50, s50, 0x100
	s_addc_u32 s51, s51, 0
	s_add_u32 s77, s77, 0x100
	s_addc_u32 s82, s82, 0
	s_cmp_gt_u32 s12, 13
	s_cbranch_scc0 .LBB0_986
	s_and_b64 vcc, exec, s[14:15]
	s_cbranch_vccz .LBB0_989
	s_barrier

; #define PG8_STAGE(bufoff, gbase, voff) do { _Pragma("unroll") for (int _i = 0; _i < 2; ++_i) \
;         __builtin_amdgcn_global_load_lds((const unsigned*)((const char*)(gbase) + (voff)[_i]), (PG8_LAS unsigned*)(lds + (bufoff) + ldsw + _i * 8192), 16, 0, 0); } while (0)
; #define PG8_LDA(dst, b, h) do { _Pragma("unroll") for (int m = 0; m < 4; ++m) _Pragma("unroll") for (int k = 0; k < 2; ++k) dst[m][k] = *(const PG8_LAS bf16x8*)(lds + PG8_SA(b, h) + aoff + m * 2048 + k * 1024); } while (0)
; #define PG8_LDB(dst, b, h) do { _Pragma("unroll") for (int n = 0; n < 2; ++n) _Pragma("unroll") for (int k = 0; k < 2; ++k) dst[n][k] = *(const PG8_LAS bf16x8*)(lds + PG8_SB(b, h) + boff + n * 2048 + k * 1024); } while (0)
; #define PG8_MMA(ai, bj, At, Bt) do { __builtin_amdgcn_s_setprio(1); _Pragma("unroll") for (int m = 0; m < 4; ++m) _Pragma("unroll") for (int n = 0; n < 2; ++n) _Pragma("unroll") for (int k = 0; k < 2; ++k) \
;         acc[ai][bj][m][n] = __builtin_amdgcn_mfma_f32_16x16x32_f16(Bt[n][k], At[m][k], acc[ai][bj][m][n], 0, 0, 0); __builtin_amdgcn_s_setprio(0); } while (0)
; #define PG8_WAIT_V(n) asm volatile("s_waitcnt vmcnt(" #n ")" ::: "memory")
; #define PG8_WAIT_L(n) asm volatile("s_waitcnt lgkmcnt(" #n ")" ::: "memory")
; #define PG8_BAR __builtin_amdgcn_s_barrier()
; #define PG8_SCHED __builtin_amdgcn_sched_barrier(0)
; template <class Epi, class Sched, bool ALIGN_EPI = false, bool SP2 = false>
; __device__ __forceinline__ void gemm_phase(PG8_LAS unsigned char* lds, const Gemm g, const Sched& S, const Epi& E) {
;     ...
;         for (int t = 0; t < nt; t += 2) {
;             const bool last = (t == nt - 2);
;             const char* a1 = cA + (size_t)(t + 1) * kstep;
;             const char* a2 = last ? nA : cA + (size_t)(t + 2) * kstep; const char* b2 = last ? nB : cB + (size_t)(t + 2) * kstep;
;             const char* a3 = a2 + kstep; const char* b3 = b2 + kstep;
;             if (last && has_next) S.a_ready(nxt);
;             if constexpr (SP2) {
;             PG8_LDB(B0, 0, 0); PG8_LDB(B1, 0, 1); PG8_SCHED; PG8_LDA(At, 0, 0); PG8_STAGE(PG8_SA(1, 1), a1 + hstep, voffA);
;             PG8_WAIT_V(8); PG8_WAIT_L(0); PG8_BAR; PG8_MMA(0, 0, At, B0); PG8_MMA(0, 1, At, B1); PG8_BAR; PG8_SCHED;
;             PG8_LDA(At, 0, 1); PG8_STAGE(PG8_SB(0, 0), b2, voffB); PG8_STAGE(PG8_SB(0, 1), b2 + hstep, voffB); PG8_STAGE(PG8_SA(0, 0), a2, voffA);
.LBB0_1134:
	s_add_u32 s13, vcc_lo, 0xfff00080
	s_addc_u32 s22, vcc_hi, -1
	s_add_i32 s92, 0, 0x10000
	s_cmp_eq_u32 s12, 60
	s_cselect_b32 s25, s29, s22
	s_cselect_b32 s24, s51, s13
	v_add_u32_e32 v1, s92, v222
	s_cselect_b32 s23, s43, s77
	s_cselect_b32 s22, s58, s76
	s_add_i32 s13, 0, 0x14000
	ds_read_b128 v[66:69], v1
	ds_read_b128 v[70:73], v1 offset:1024
	ds_read_b128 v[78:81], v1 offset:2048
	ds_read_b128 v[82:85], v1 offset:3072
	v_add_u32_e32 v1, s13, v222
	ds_read_b128 v[86:89], v1
	ds_read_b128 v[90:93], v1 offset:1024
	ds_read_b128 v[94:97], v1 offset:2048
	ds_read_b128 v[98:101], v1 offset:3072
	v_lshl_add_u64 v[208:209], vcc, 0, v[196:197]
	s_add_i32 m0, s11, 0xc000
	ds_read_b128 v[158:161], v225
	ds_read_b128 v[170:173], v225 offset:1024
	ds_read_b128 v[174:177], v225 offset:2048
	ds_read_b128 v[178:181], v225 offset:3072
	ds_read_b128 v[182:185], v225 offset:4096
	ds_read_b128 v[186:189], v225 offset:5120
	ds_read_b128 v[200:203], v225 offset:6144
	ds_read_b128 v[204:207], v225 offset:7168
	global_load_lds_dwordx4 v[208:209], off
	v_lshl_add_u64 v[208:209], vcc, 0, v[198:199]
	s_add_i32 m0, s11, 0xe000
	s_nop 0
	global_load_lds_dwordx4 v[208:209], off
	s_waitcnt vmcnt(8)
	s_waitcnt lgkmcnt(0)
	s_barrier
	v_mfma_f32_16x16x32_f16 v[166:169], v[66:69], v[158:161], v[166:169]
	v_mfma_f32_16x16x32_f16 v[162:165], v[78:81], v[158:161], v[162:165]
	v_mfma_f32_16x16x32_f16 v[146:149], v[66:69], v[174:177], v[146:149]
	v_mfma_f32_16x16x32_f16 v[142:145], v[78:81], v[174:177], v[142:145]
	v_mfma_f32_16x16x32_f16 v[130:133], v[66:69], v[182:185], v[130:133]
	v_mfma_f32_16x16x32_f16 v[126:129], v[78:81], v[182:185], v[126:129]
	v_mfma_f32_16x16x32_f16 v[114:117], v[66:69], v[200:203], v[114:117]
	v_mfma_f32_16x16x32_f16 v[110:113], v[78:81], v[200:203], v[110:113]
	v_mfma_f32_16x16x32_f16 v[166:169], v[70:73], v[170:173], v[166:169]
	v_mfma_f32_16x16x32_f16 v[162:165], v[82:85], v[170:173], v[162:165]
	v_mfma_f32_16x16x32_f16 v[146:149], v[70:73], v[178:181], v[146:149]
	v_mfma_f32_16x16x32_f16 v[142:145], v[82:85], v[178:181], v[142:145]
	v_mfma_f32_16x16x32_f16 v[130:133], v[70:73], v[186:189], v[130:133]
	v_mfma_f32_16x16x32_f16 v[126:129], v[82:85], v[186:189], v[126:129]
	v_mfma_f32_16x16x32_f16 v[114:117], v[70:73], v[204:207], v[114:117]
	v_mfma_f32_16x16x32_f16 v[110:113], v[82:85], v[204:207], v[110:113]
	v_mfma_f32_16x16x32_f16 v[154:157], v[86:89], v[158:161], v[154:157]
	v_mfma_f32_16x16x32_f16 v[150:153], v[94:97], v[158:161], v[150:153]
	v_mfma_f32_16x16x32_f16 v[138:141], v[86:89], v[174:177], v[138:141]
	v_mfma_f32_16x16x32_f16 v[134:137], v[94:97], v[174:177], v[134:137]
	v_mfma_f32_16x16x32_f16 v[122:125], v[86:89], v[182:185], v[122:125]
	v_mfma_f32_16x16x32_f16 v[118:121], v[94:97], v[182:185], v[118:121]
	v_mfma_f32_16x16x32_f16 v[106:109], v[86:89], v[200:203], v[106:109]
	v_mfma_f32_16x16x32_f16 v[102:105], v[94:97], v[200:203], v[102:105]
	v_mfma_f32_16x16x32_f16 v[154:157], v[90:93], v[170:173], v[154:157]
	v_mfma_f32_16x16x32_f16 v[150:153], v[98:101], v[170:173], v[150:153]
	v_mfma_f32_16x16x32_f16 v[138:141], v[90:93], v[178:181], v[138:141]
	v_mfma_f32_16x16x32_f16 v[134:137], v[98:101], v[178:181], v[134:137]
	v_mfma_f32_16x16x32_f16 v[122:125], v[90:93], v[186:189], v[122:125]
	v_mfma_f32_16x16x32_f16 v[118:121], v[98:101], v[186:189], v[118:121]
	v_mfma_f32_16x16x32_f16 v[106:109], v[90:93], v[204:207], v[106:109]
	v_mfma_f32_16x16x32_f16 v[102:105], v[98:101], v[204:207], v[102:105]
	s_barrier
	s_add_i32 s92, s92, s5
	v_lshl_add_u64 v[208:209], s[22:23], 0, v[192:193]
	s_mov_b32 m0, s92
	ds_read_b128 v[158:161], v225 offset:16384
	ds_read_b128 v[170:173], v225 offset:17408
	ds_read_b128 v[174:177], v225 offset:18432
	ds_read_b128 v[178:181], v225 offset:19456
	ds_read_b128 v[182:185], v225 offset:20480
	ds_read_b128 v[186:189], v225 offset:21504
	ds_read_b128 v[200:203], v225 offset:22528
	ds_read_b128 v[204:207], v225 offset:23552
	global_load_lds_dwordx4 v[208:209], off
	s_add_i32 m0, s92, 0x2000
	s_add_u32 s92, s22, 0x100000
	v_lshl_add_u64 v[210:211], s[22:23], 0, v[14:15]
	s_addc_u32 s93, s23, 0
	s_add_i32 s13, s13, s5
	global_load_lds_dwordx4 v[210:211], off
	v_lshl_add_u64 v[212:213], s[92:93], 0, v[192:193]
	s_mov_b32 m0, s13
	v_lshl_add_u64 v[214:215], s[24:25], 0, v[190:191]
	global_load_lds_dwordx4 v[212:213], off
	v_lshl_add_u64 v[212:213], s[92:93], 0, v[14:15]
	s_add_i32 m0, s13, 0x2000
	s_nop 0
	global_load_lds_dwordx4 v[212:213], off
	v_lshl_add_u64 v[212:213], s[24:25], 0, v[194:195]
	s_mov_b32 m0, s11
	s_nop 0
	global_load_lds_dwordx4 v[212:213], off
	s_mov_b32 m0, s28
	s_nop 0
	global_load_lds_dwordx4 v[214:215], off
	s_waitcnt vmcnt(8)
	s_waitcnt lgkmcnt(0)
	s_barrier
; #define PG8_STAGE(bufoff, gbase, voff) do { _Pragma("unroll") for (int _i = 0; _i < 2; ++_i) \
;         __builtin_amdgcn_global_load_lds((const unsigned*)((const char*)(gbase) + (voff)[_i]), (PG8_LAS unsigned*)(lds + (bufoff) + ldsw + _i * 8192), 16, 0, 0); } while (0)
; #define PG8_LDA(dst, b, h) do { _Pragma("unroll") for (int m = 0; m < 4; ++m) _Pragma("unroll") for (int k = 0; k < 2; ++k) dst[m][k] = *(const PG8_LAS bf16x8*)(lds + PG8_SA(b, h) + aoff + m * 2048 + k * 1024); } while (0)
; #define PG8_LDB(dst, b, h) do { _Pragma("unroll") for (int n = 0; n < 2; ++n) _Pragma("unroll") for (int k = 0; k < 2; ++k) dst[n][k] = *(const PG8_LAS bf16x8*)(lds + PG8_SB(b, h) + boff + n * 2048 + k * 1024); } while (0)
; #define PG8_MMA(ai, bj, At, Bt) do { __builtin_amdgcn_s_setprio(1); _Pragma("unroll") for (int m = 0; m < 4; ++m) _Pragma("unroll") for (int n = 0; n < 2; ++n) _Pragma("unroll") for (int k = 0; k < 2; ++k) \
;         acc[ai][bj][m][n] = __builtin_amdgcn_mfma_f32_16x16x32_f16(Bt[n][k], At[m][k], acc[ai][bj][m][n], 0, 0, 0); __builtin_amdgcn_s_setprio(0); } while (0)
; #define PG8_WAIT_V(n) asm volatile("s_waitcnt vmcnt(" #n ")" ::: "memory")
; #define PG8_WAIT_L(n) asm volatile("s_waitcnt lgkmcnt(" #n ")" ::: "memory")
; #define PG8_BAR __builtin_amdgcn_s_barrier()
; #define PG8_SCHED __builtin_amdgcn_sched_barrier(0)
; template <class Epi, class Sched, bool ALIGN_EPI = false, bool SP2 = false>
; __device__ __forceinline__ void gemm_phase(PG8_LAS unsigned char* lds, const Gemm g, const Sched& S, const Epi& E) {
;     ...
;             PG8_LDA(At, 0, 1); PG8_STAGE(PG8_SB(0, 0), b2, voffB); PG8_STAGE(PG8_SB(0, 1), b2 + hstep, voffB); PG8_STAGE(PG8_SA(0, 0), a2, voffA);
;             PG8_WAIT_V(8); PG8_WAIT_L(0); PG8_BAR; PG8_MMA(1, 0, At, B0); PG8_MMA(1, 1, At, B1); PG8_BAR; PG8_SCHED;
;             PG8_LDB(B0, 1, 0); PG8_LDB(B1, 1, 1); PG8_SCHED; PG8_LDA(At, 1, 0); PG8_STAGE(PG8_SA(0, 1), a2 + hstep, voffA);
;             PG8_WAIT_V(8); PG8_WAIT_L(0); PG8_BAR; PG8_MMA(0, 0, At, B0); PG8_MMA(0, 1, At, B1); PG8_BAR; PG8_SCHED;
	v_mfma_f32_16x16x32_f16 v[74:77], v[66:69], v[158:161], v[74:77]
	v_mfma_f32_16x16x32_f16 v[62:65], v[78:81], v[158:161], v[62:65]
	v_mfma_f32_16x16x32_f16 v[50:53], v[66:69], v[174:177], v[50:53]
	v_mfma_f32_16x16x32_f16 v[46:49], v[78:81], v[174:177], v[46:49]
	v_mfma_f32_16x16x32_f16 v[34:37], v[66:69], v[182:185], v[34:37]
	v_mfma_f32_16x16x32_f16 v[30:33], v[78:81], v[182:185], v[30:33]
	v_mfma_f32_16x16x32_f16 v[18:21], v[66:69], v[200:203], v[18:21]
	v_mfma_f32_16x16x32_f16 v[10:13], v[78:81], v[200:203], v[10:13]
	v_mfma_f32_16x16x32_f16 v[74:77], v[70:73], v[170:173], v[74:77]
	v_mfma_f32_16x16x32_f16 v[62:65], v[82:85], v[170:173], v[62:65]
	v_mfma_f32_16x16x32_f16 v[50:53], v[70:73], v[178:181], v[50:53]
	v_mfma_f32_16x16x32_f16 v[46:49], v[82:85], v[178:181], v[46:49]
	v_mfma_f32_16x16x32_f16 v[34:37], v[70:73], v[186:189], v[34:37]
	v_mfma_f32_16x16x32_f16 v[30:33], v[82:85], v[186:189], v[30:33]
	v_mfma_f32_16x16x32_f16 v[18:21], v[70:73], v[204:207], v[18:21]
	v_mfma_f32_16x16x32_f16 v[10:13], v[82:85], v[204:207], v[10:13]
	v_mfma_f32_16x16x32_f16 v[58:61], v[86:89], v[158:161], v[58:61]
	v_mfma_f32_16x16x32_f16 v[54:57], v[94:97], v[158:161], v[54:57]
	v_mfma_f32_16x16x32_f16 v[42:45], v[86:89], v[174:177], v[42:45]
	v_mfma_f32_16x16x32_f16 v[38:41], v[94:97], v[174:177], v[38:41]
	v_mfma_f32_16x16x32_f16 v[26:29], v[86:89], v[182:185], v[26:29]
	v_mfma_f32_16x16x32_f16 v[22:25], v[94:97], v[182:185], v[22:25]
	v_mfma_f32_16x16x32_f16 v[6:9], v[86:89], v[200:203], v[6:9]
	v_mfma_f32_16x16x32_f16 v[2:5], v[94:97], v[200:203], v[2:5]
	v_mfma_f32_16x16x32_f16 v[58:61], v[90:93], v[170:173], v[58:61]
	v_mfma_f32_16x16x32_f16 v[54:57], v[98:101], v[170:173], v[54:57]
	v_mfma_f32_16x16x32_f16 v[42:45], v[90:93], v[178:181], v[42:45]
	v_mfma_f32_16x16x32_f16 v[38:41], v[98:101], v[178:181], v[38:41]
	v_mfma_f32_16x16x32_f16 v[26:29], v[90:93], v[186:189], v[26:29]
	v_mfma_f32_16x16x32_f16 v[22:25], v[98:101], v[186:189], v[22:25]
	v_mfma_f32_16x16x32_f16 v[6:9], v[90:93], v[204:207], v[6:9]
	v_mfma_f32_16x16x32_f16 v[2:5], v[98:101], v[204:207], v[2:5]
	s_barrier
	s_add_i32 s13, 0, 0x18000
	v_add_u32_e32 v1, s13, v222
	s_add_i32 s92, 0, 0x1c000
	ds_read_b128 v[66:69], v1
	ds_read_b128 v[70:73], v1 offset:1024
	ds_read_b128 v[78:81], v1 offset:2048
	ds_read_b128 v[82:85], v1 offset:3072
	v_add_u32_e32 v1, s92, v222
	ds_read_b128 v[86:89], v1
	ds_read_b128 v[90:93], v1 offset:1024
	ds_read_b128 v[94:97], v1 offset:2048
	ds_read_b128 v[98:101], v1 offset:3072
	s_add_u32 s24, s24, 0x100000
	s_addc_u32 s25, s25, 0
	s_mov_b32 m0, s33
	v_lshl_add_u64 v[218:219], s[24:25], 0, v[194:195]
	ds_read_b128 v[158:161], v225 offset:32768
	ds_read_b128 v[170:173], v225 offset:33792
	ds_read_b128 v[174:177], v225 offset:34816
	ds_read_b128 v[178:181], v225 offset:35840
	ds_read_b128 v[182:185], v225 offset:36864
	ds_read_b128 v[186:189], v225 offset:37888
	ds_read_b128 v[200:203], v225 offset:38912
	ds_read_b128 v[204:207], v225 offset:39936
	global_load_lds_dwordx4 v[218:219], off
	v_lshl_add_u64 v[218:219], s[24:25], 0, v[190:191]
	s_mov_b32 m0, s49
	s_nop 0
	global_load_lds_dwordx4 v[218:219], off
	s_waitcnt vmcnt(8)
	s_waitcnt lgkmcnt(0)
	s_barrier
	v_mfma_f32_16x16x32_f16 v[166:169], v[66:69], v[158:161], v[166:169]
	v_mfma_f32_16x16x32_f16 v[162:165], v[78:81], v[158:161], v[162:165]
	v_mfma_f32_16x16x32_f16 v[146:149], v[66:69], v[174:177], v[146:149]
	v_mfma_f32_16x16x32_f16 v[142:145], v[78:81], v[174:177], v[142:145]
	v_mfma_f32_16x16x32_f16 v[130:133], v[66:69], v[182:185], v[130:133]
	v_mfma_f32_16x16x32_f16 v[126:129], v[78:81], v[182:185], v[126:129]
	v_mfma_f32_16x16x32_f16 v[114:117], v[66:69], v[200:203], v[114:117]
	v_mfma_f32_16x16x32_f16 v[110:113], v[78:81], v[200:203], v[110:113]
	v_mfma_f32_16x16x32_f16 v[166:169], v[70:73], v[170:173], v[166:169]
	v_mfma_f32_16x16x32_f16 v[162:165], v[82:85], v[170:173], v[162:165]
	v_mfma_f32_16x16x32_f16 v[146:149], v[70:73], v[178:181], v[146:149]
	v_mfma_f32_16x16x32_f16 v[142:145], v[82:85], v[178:181], v[142:145]
	v_mfma_f32_16x16x32_f16 v[130:133], v[70:73], v[186:189], v[130:133]
	v_mfma_f32_16x16x32_f16 v[126:129], v[82:85], v[186:189], v[126:129]
	v_mfma_f32_16x16x32_f16 v[114:117], v[70:73], v[204:207], v[114:117]
	v_mfma_f32_16x16x32_f16 v[110:113], v[82:85], v[204:207], v[110:113]
	v_mfma_f32_16x16x32_f16 v[154:157], v[86:89], v[158:161], v[154:157]
	v_mfma_f32_16x16x32_f16 v[150:153], v[94:97], v[158:161], v[150:153]
	v_mfma_f32_16x16x32_f16 v[138:141], v[86:89], v[174:177], v[138:141]
	v_mfma_f32_16x16x32_f16 v[134:137], v[94:97], v[174:177], v[134:137]
	v_mfma_f32_16x16x32_f16 v[122:125], v[86:89], v[182:185], v[122:125]
	v_mfma_f32_16x16x32_f16 v[118:121], v[94:97], v[182:185], v[118:121]
	v_mfma_f32_16x16x32_f16 v[106:109], v[86:89], v[200:203], v[106:109]
	v_mfma_f32_16x16x32_f16 v[102:105], v[94:97], v[200:203], v[102:105]
	v_mfma_f32_16x16x32_f16 v[154:157], v[90:93], v[170:173], v[154:157]
	v_mfma_f32_16x16x32_f16 v[150:153], v[98:101], v[170:173], v[150:153]
	v_mfma_f32_16x16x32_f16 v[138:141], v[90:93], v[178:181], v[138:141]
	v_mfma_f32_16x16x32_f16 v[134:137], v[98:101], v[178:181], v[134:137]
	v_mfma_f32_16x16x32_f16 v[122:125], v[90:93], v[186:189], v[122:125]
	v_mfma_f32_16x16x32_f16 v[118:121], v[98:101], v[186:189], v[118:121]
	v_mfma_f32_16x16x32_f16 v[106:109], v[90:93], v[204:207], v[106:109]
	v_mfma_f32_16x16x32_f16 v[102:105], v[98:101], v[204:207], v[102:105]
	s_barrier
; #define PG8_STAGE(bufoff, gbase, voff) do { _Pragma("unroll") for (int _i = 0; _i < 2; ++_i) \
;         __builtin_amdgcn_global_load_lds((const unsigned*)((const char*)(gbase) + (voff)[_i]), (PG8_LAS unsigned*)(lds + (bufoff) + ldsw + _i * 8192), 16, 0, 0); } while (0)
; #define PG8_LDA(dst, b, h) do { _Pragma("unroll") for (int m = 0; m < 4; ++m) _Pragma("unroll") for (int k = 0; k < 2; ++k) dst[m][k] = *(const PG8_LAS bf16x8*)(lds + PG8_SA(b, h) + aoff + m * 2048 + k * 1024); } while (0)
; #define PG8_WAIT_V(n) asm volatile("s_waitcnt vmcnt(" #n ")" ::: "memory")
; template <class Epi, class Sched, bool ALIGN_EPI = false, bool SP2 = false>
; __device__ __forceinline__ void gemm_phase(PG8_LAS unsigned char* lds, const Gemm g, const Sched& S, const Epi& E) {
;     ...
;             PG8_LDA(At, 1, 1); PG8_STAGE(PG8_SB(1, 0), b3, voffB); PG8_STAGE(PG8_SB(1, 1), b3 + hstep, voffB); PG8_STAGE(PG8_SA(1, 0), a3, voffA);
;             PG8_WAIT_V(8); PG8_WAIT_L(0); PG8_BAR; PG8_MMA(1, 0, At, B0); PG8_MMA(1, 1, At, B1); PG8_BAR; PG8_SCHED;
;             } else {
;             PG8_LDB(B0, 0, 0); PG8_SCHED; PG8_LDA(At, 0, 0); PG8_STAGE(PG8_SA(1, 1), a1 + hstep, voffA);
;             PG8_WAIT_L(8); PG8_BAR; PG8_WAIT_L(0); PG8_MMA(0, 0, At, B0); PG8_BAR; PG8_SCHED;
;             PG8_LDB(B1, 0, 1); PG8_STAGE(PG8_SB(0, 0), b2, voffB);
;             PG8_BAR; PG8_WAIT_L(0); PG8_MMA(0, 1, At, B1); PG8_BAR;
;             PG8_LDA(At, 0, 1); PG8_STAGE(PG8_SA(0, 0), a2, voffA);
;             PG8_BAR; PG8_WAIT_L(0); PG8_MMA(1, 0, At, B0); PG8_BAR; PG8_SCHED;
;             PG8_STAGE(PG8_SB(0, 1), b2 + hstep, voffB);
;             PG8_WAIT_V(6); PG8_BAR; PG8_MMA(1, 1, At, B1); PG8_BAR;
;             PG8_LDB(B0, 1, 0); PG8_SCHED; PG8_LDA(At, 1, 0); PG8_STAGE(PG8_SA(0, 1), a2 + hstep, voffA);
;             PG8_WAIT_L(8); PG8_BAR; PG8_WAIT_L(0); PG8_MMA(0, 0, At, B0); PG8_BAR; PG8_SCHED;
;             PG8_LDB(B1, 1, 1); PG8_STAGE(PG8_SB(1, 0), b3, voffB);
;             PG8_BAR; PG8_WAIT_L(0); PG8_MMA(0, 1, At, B1); PG8_BAR;
;             PG8_LDA(At, 1, 1); PG8_STAGE(PG8_SA(1, 0), a3, voffA);
;             PG8_BAR; PG8_WAIT_L(0); PG8_MMA(1, 0, At, B0); PG8_BAR; PG8_SCHED;
;             PG8_STAGE(PG8_SB(1, 1), b3 + hstep, voffB);
;             PG8_WAIT_V(6); PG8_BAR; PG8_MMA(1, 1, At, B1); PG8_BAR;
;             }
;         }
;         if constexpr (ALIGN_EPI) { if (wr == 0) PG8_BAR; }
	s_add_i32 s13, s13, s5
	v_lshl_add_u64 v[208:209], v[208:209], 0, s[34:35]
	s_mov_b32 m0, s13
	ds_read_b128 v[158:161], v225 offset:49152
	ds_read_b128 v[170:173], v225 offset:50176
	ds_read_b128 v[174:177], v225 offset:51200
	ds_read_b128 v[178:181], v225 offset:52224
	ds_read_b128 v[182:185], v225 offset:53248
	ds_read_b128 v[186:189], v225 offset:54272
	ds_read_b128 v[200:203], v225 offset:55296
	ds_read_b128 v[204:207], v225 offset:56320
	global_load_lds_dwordx4 v[208:209], off
	s_add_i32 m0, s13, 0x2000
	s_add_u32 s22, s22, 0x100080
	v_lshl_add_u64 v[208:209], v[210:211], 0, s[34:35]
	s_addc_u32 s23, s23, 0
	s_add_i32 s13, s92, s5
	global_load_lds_dwordx4 v[208:209], off
	v_lshl_add_u64 v[208:209], s[22:23], 0, v[192:193]
	s_mov_b32 m0, s13
	s_nop 0
	global_load_lds_dwordx4 v[208:209], off
	v_lshl_add_u64 v[208:209], s[22:23], 0, v[14:15]
	s_add_i32 m0, s13, 0x2000
	s_nop 0
	global_load_lds_dwordx4 v[208:209], off
	v_lshl_add_u64 v[208:209], v[212:213], 0, s[34:35]
	s_mov_b32 m0, s72
	s_nop 0
	global_load_lds_dwordx4 v[208:209], off
	v_lshl_add_u64 v[208:209], v[214:215], 0, s[34:35]
	s_mov_b32 m0, s73
	s_nop 0
	global_load_lds_dwordx4 v[208:209], off
	s_waitcnt vmcnt(8)
	s_waitcnt lgkmcnt(0)
	s_barrier
	v_mfma_f32_16x16x32_f16 v[74:77], v[66:69], v[158:161], v[74:77]
	v_mfma_f32_16x16x32_f16 v[62:65], v[78:81], v[158:161], v[62:65]
	v_mfma_f32_16x16x32_f16 v[50:53], v[66:69], v[174:177], v[50:53]
	v_mfma_f32_16x16x32_f16 v[46:49], v[78:81], v[174:177], v[46:49]
	v_mfma_f32_16x16x32_f16 v[34:37], v[66:69], v[182:185], v[34:37]
	v_mfma_f32_16x16x32_f16 v[30:33], v[78:81], v[182:185], v[30:33]
	v_mfma_f32_16x16x32_f16 v[18:21], v[66:69], v[200:203], v[18:21]
	v_mfma_f32_16x16x32_f16 v[10:13], v[78:81], v[200:203], v[10:13]
	v_mfma_f32_16x16x32_f16 v[74:77], v[70:73], v[170:173], v[74:77]
	v_mfma_f32_16x16x32_f16 v[62:65], v[82:85], v[170:173], v[62:65]
	v_mfma_f32_16x16x32_f16 v[50:53], v[70:73], v[178:181], v[50:53]
	v_mfma_f32_16x16x32_f16 v[46:49], v[82:85], v[178:181], v[46:49]
	v_mfma_f32_16x16x32_f16 v[34:37], v[70:73], v[186:189], v[34:37]
	v_mfma_f32_16x16x32_f16 v[30:33], v[82:85], v[186:189], v[30:33]
	v_mfma_f32_16x16x32_f16 v[18:21], v[70:73], v[204:207], v[18:21]
	v_mfma_f32_16x16x32_f16 v[10:13], v[82:85], v[204:207], v[10:13]
	v_mfma_f32_16x16x32_f16 v[58:61], v[86:89], v[158:161], v[58:61]
	v_mfma_f32_16x16x32_f16 v[54:57], v[94:97], v[158:161], v[54:57]
	v_mfma_f32_16x16x32_f16 v[42:45], v[86:89], v[174:177], v[42:45]
	v_mfma_f32_16x16x32_f16 v[38:41], v[94:97], v[174:177], v[38:41]
	v_mfma_f32_16x16x32_f16 v[26:29], v[86:89], v[182:185], v[26:29]
	v_mfma_f32_16x16x32_f16 v[22:25], v[94:97], v[182:185], v[22:25]
	v_mfma_f32_16x16x32_f16 v[6:9], v[86:89], v[200:203], v[6:9]
	v_mfma_f32_16x16x32_f16 v[2:5], v[94:97], v[200:203], v[2:5]
	v_mfma_f32_16x16x32_f16 v[58:61], v[90:93], v[170:173], v[58:61]
	v_mfma_f32_16x16x32_f16 v[54:57], v[98:101], v[170:173], v[54:57]
	v_mfma_f32_16x16x32_f16 v[42:45], v[90:93], v[178:181], v[42:45]
	v_mfma_f32_16x16x32_f16 v[38:41], v[98:101], v[178:181], v[38:41]
	v_mfma_f32_16x16x32_f16 v[26:29], v[90:93], v[186:189], v[26:29]
	v_mfma_f32_16x16x32_f16 v[22:25], v[98:101], v[186:189], v[22:25]
	v_mfma_f32_16x16x32_f16 v[6:9], v[90:93], v[204:207], v[6:9]
	v_mfma_f32_16x16x32_f16 v[2:5], v[98:101], v[204:207], v[2:5]
	s_barrier
	s_add_i32 s12, s12, 2
	s_add_u32 vcc_lo, vcc_lo, 0x100
	s_addc_u32 vcc_hi, vcc_hi, 0
	s_add_u32 s76, s76, 0x100
	s_addc_u32 s77, s77, 0
	s_cmp_gt_u32 s12, 61
	s_cbranch_scc0 .LBB0_1134
	s_and_b64 vcc, exec, s[40:41]
	s_cbranch_vccz .LBB0_1137
	s_barrier
